# as previous but the per-MFMA-block s_setprio flips of the GEMM K-loops deleted (A/B of the template's priority toggles)
# speedup vs baseline: 1.0048x; 1.0048x over previous
.LBB0_247:
	s_add_u32 s4, s44, 0xfffc0080
	s_addc_u32 s5, s45, -1
	s_add_i32 s62, 0, 0x10000
	s_cmp_eq_u32 s61, 12
	s_cselect_b32 s5, s39, s5
	s_cselect_b32 s4, s38, s4
	v_add_u32_e32 v138, s62, v141
	s_cselect_b32 s47, s43, s9
	s_cselect_b32 s46, s42, s8
	s_add_i32 s64, 0, 0x14000
	ds_read_b128 v[144:147], v138
	ds_read_b128 v[148:151], v138 offset:1024
	ds_read_b128 v[152:155], v138 offset:2048
	ds_read_b128 v[156:159], v138 offset:3072
	v_add_u32_e32 v138, s64, v141
	ds_read_b128 v[160:163], v138
	ds_read_b128 v[164:167], v138 offset:1024
	ds_read_b128 v[168:171], v138 offset:2048
	ds_read_b128 v[182:185], v138 offset:3072
	v_lshl_add_u64 v[138:139], s[44:45], 0, v[134:135]
	s_add_i32 m0, s13, 0xc000
	ds_read_b128 v[186:189], v143
	ds_read_b128 v[190:193], v143 offset:1024
	ds_read_b128 v[194:197], v143 offset:2048
	ds_read_b128 v[198:201], v143 offset:3072
	ds_read_b128 v[214:217], v143 offset:4096
	ds_read_b128 v[218:221], v143 offset:5120
	ds_read_b128 v[222:225], v143 offset:6144
	ds_read_b128 v[226:229], v143 offset:7168
	global_load_lds_dwordx4 v[138:139], off
	v_lshl_add_u64 v[138:139], s[44:45], 0, v[136:137]
	s_add_i32 m0, s13, 0xe000
	s_nop 0
	global_load_lds_dwordx4 v[138:139], off
	s_waitcnt vmcnt(8)
	s_waitcnt lgkmcnt(0)
	s_barrier
	s_waitcnt lgkmcnt(0)
	v_mfma_f32_16x16x32_bf16 v[124:127], v[144:147], v[186:189], v[124:127]
	v_mfma_f32_16x16x32_bf16 v[120:123], v[152:155], v[186:189], v[120:123]
	v_mfma_f32_16x16x32_bf16 v[112:115], v[144:147], v[194:197], v[112:115]
	v_mfma_f32_16x16x32_bf16 v[104:107], v[152:155], v[194:197], v[104:107]
	v_mfma_f32_16x16x32_bf16 v[96:99], v[144:147], v[214:217], v[96:99]
	v_mfma_f32_16x16x32_bf16 v[88:91], v[152:155], v[214:217], v[88:91]
	v_mfma_f32_16x16x32_bf16 v[80:83], v[144:147], v[222:225], v[80:83]
	v_mfma_f32_16x16x32_bf16 v[72:75], v[152:155], v[222:225], v[72:75]
	v_mfma_f32_16x16x32_bf16 v[124:127], v[148:151], v[190:193], v[124:127]
	v_mfma_f32_16x16x32_bf16 v[120:123], v[156:159], v[190:193], v[120:123]
	v_mfma_f32_16x16x32_bf16 v[112:115], v[148:151], v[198:201], v[112:115]
	v_mfma_f32_16x16x32_bf16 v[104:107], v[156:159], v[198:201], v[104:107]
	v_mfma_f32_16x16x32_bf16 v[96:99], v[148:151], v[218:221], v[96:99]
	v_mfma_f32_16x16x32_bf16 v[88:91], v[156:159], v[218:221], v[88:91]
	v_mfma_f32_16x16x32_bf16 v[80:83], v[148:151], v[226:229], v[80:83]
	v_mfma_f32_16x16x32_bf16 v[72:75], v[156:159], v[226:229], v[72:75]
	v_mfma_f32_16x16x32_bf16 v[116:119], v[160:163], v[186:189], v[116:119]
	v_mfma_f32_16x16x32_bf16 v[108:111], v[168:171], v[186:189], v[108:111]
	v_mfma_f32_16x16x32_bf16 v[100:103], v[160:163], v[194:197], v[100:103]
	v_mfma_f32_16x16x32_bf16 v[92:95], v[168:171], v[194:197], v[92:95]
	v_mfma_f32_16x16x32_bf16 v[84:87], v[160:163], v[214:217], v[84:87]
	v_mfma_f32_16x16x32_bf16 v[76:79], v[168:171], v[214:217], v[76:79]
	v_mfma_f32_16x16x32_bf16 v[68:71], v[160:163], v[222:225], v[68:71]
	v_mfma_f32_16x16x32_bf16 v[64:67], v[168:171], v[222:225], v[64:67]
	v_mfma_f32_16x16x32_bf16 v[116:119], v[164:167], v[190:193], v[116:119]
	v_mfma_f32_16x16x32_bf16 v[108:111], v[182:185], v[190:193], v[108:111]
	v_mfma_f32_16x16x32_bf16 v[100:103], v[164:167], v[198:201], v[100:103]
	v_mfma_f32_16x16x32_bf16 v[92:95], v[182:185], v[198:201], v[92:95]
	v_mfma_f32_16x16x32_bf16 v[84:87], v[164:167], v[218:221], v[84:87]
	v_mfma_f32_16x16x32_bf16 v[76:79], v[182:185], v[218:221], v[76:79]
	v_mfma_f32_16x16x32_bf16 v[68:71], v[164:167], v[226:229], v[68:71]
	v_mfma_f32_16x16x32_bf16 v[64:67], v[182:185], v[226:229], v[64:67]
	s_barrier
	s_add_i32 s62, s62, s11
	v_lshl_add_u64 v[138:139], s[46:47], 0, v[172:173]
	s_mov_b32 m0, s62
	ds_read_b128 v[186:189], v143 offset:16384
	ds_read_b128 v[190:193], v143 offset:17408
	ds_read_b128 v[194:197], v143 offset:18432
	ds_read_b128 v[198:201], v143 offset:19456
	ds_read_b128 v[214:217], v143 offset:20480
	ds_read_b128 v[218:221], v143 offset:21504
	ds_read_b128 v[222:225], v143 offset:22528
	ds_read_b128 v[226:229], v143 offset:23552
	global_load_lds_dwordx4 v[138:139], off
	s_add_i32 m0, s62, 0x2000
	s_add_u32 s62, s46, 0x40000
	v_lshl_add_u64 v[202:203], s[46:47], 0, v[128:129]
	s_addc_u32 s63, s47, 0
	s_add_i32 s64, s64, s11
	global_load_lds_dwordx4 v[202:203], off
	v_lshl_add_u64 v[230:231], s[62:63], 0, v[172:173]
	s_mov_b32 m0, s64
	v_lshl_add_u64 v[232:233], s[4:5], 0, v[130:131]
	global_load_lds_dwordx4 v[230:231], off
	v_lshl_add_u64 v[230:231], s[62:63], 0, v[128:129]
	s_add_i32 m0, s64, 0x2000
	s_nop 0
	global_load_lds_dwordx4 v[230:231], off
	v_lshl_add_u64 v[230:231], s[4:5], 0, v[132:133]
	s_mov_b32 m0, s13
	s_nop 0
	global_load_lds_dwordx4 v[230:231], off
	s_mov_b32 m0, s26
	s_nop 0
	global_load_lds_dwordx4 v[232:233], off
	s_waitcnt vmcnt(8)
	s_waitcnt lgkmcnt(0)
	s_barrier
	s_waitcnt lgkmcnt(0)
	v_mfma_f32_16x16x32_bf16 v[60:63], v[144:147], v[186:189], v[60:63]
	v_mfma_f32_16x16x32_bf16 v[56:59], v[152:155], v[186:189], v[56:59]
	v_mfma_f32_16x16x32_bf16 v[48:51], v[144:147], v[194:197], v[48:51]
	v_mfma_f32_16x16x32_bf16 v[40:43], v[152:155], v[194:197], v[40:43]
	v_mfma_f32_16x16x32_bf16 v[32:35], v[144:147], v[214:217], v[32:35]
	v_mfma_f32_16x16x32_bf16 v[24:27], v[152:155], v[214:217], v[24:27]
	v_mfma_f32_16x16x32_bf16 v[16:19], v[144:147], v[222:225], v[16:19]
	v_mfma_f32_16x16x32_bf16 v[8:11], v[152:155], v[222:225], v[8:11]
	v_mfma_f32_16x16x32_bf16 v[60:63], v[148:151], v[190:193], v[60:63]
	v_mfma_f32_16x16x32_bf16 v[56:59], v[156:159], v[190:193], v[56:59]
	v_mfma_f32_16x16x32_bf16 v[48:51], v[148:151], v[198:201], v[48:51]
	v_mfma_f32_16x16x32_bf16 v[40:43], v[156:159], v[198:201], v[40:43]
	v_mfma_f32_16x16x32_bf16 v[32:35], v[148:151], v[218:221], v[32:35]
	v_mfma_f32_16x16x32_bf16 v[24:27], v[156:159], v[218:221], v[24:27]
	v_mfma_f32_16x16x32_bf16 v[16:19], v[148:151], v[226:229], v[16:19]
	v_mfma_f32_16x16x32_bf16 v[8:11], v[156:159], v[226:229], v[8:11]
	v_mfma_f32_16x16x32_bf16 v[52:55], v[160:163], v[186:189], v[52:55]
	v_mfma_f32_16x16x32_bf16 v[44:47], v[168:171], v[186:189], v[44:47]
	v_mfma_f32_16x16x32_bf16 v[36:39], v[160:163], v[194:197], v[36:39]
	v_mfma_f32_16x16x32_bf16 v[28:31], v[168:171], v[194:197], v[28:31]
	v_mfma_f32_16x16x32_bf16 v[20:23], v[160:163], v[214:217], v[20:23]
	v_mfma_f32_16x16x32_bf16 v[12:15], v[168:171], v[214:217], v[12:15]
	v_mfma_f32_16x16x32_bf16 v[4:7], v[160:163], v[222:225], v[4:7]
	v_mfma_f32_16x16x32_bf16 v[0:3], v[168:171], v[222:225], v[0:3]
	v_mfma_f32_16x16x32_bf16 v[52:55], v[164:167], v[190:193], v[52:55]
	v_mfma_f32_16x16x32_bf16 v[44:47], v[182:185], v[190:193], v[44:47]
	v_mfma_f32_16x16x32_bf16 v[36:39], v[164:167], v[198:201], v[36:39]
	v_mfma_f32_16x16x32_bf16 v[28:31], v[182:185], v[198:201], v[28:31]
	v_mfma_f32_16x16x32_bf16 v[20:23], v[164:167], v[218:221], v[20:23]
	v_mfma_f32_16x16x32_bf16 v[12:15], v[182:185], v[218:221], v[12:15]
	v_mfma_f32_16x16x32_bf16 v[4:7], v[164:167], v[226:229], v[4:7]
	v_mfma_f32_16x16x32_bf16 v[0:3], v[182:185], v[226:229], v[0:3]
	s_barrier
	s_add_i32 s62, 0, 0x18000
	s_add_i32 s63, 0, 0x1c000
	v_add_u32_e32 v156, s62, v141
	v_add_u32_e32 v182, s63, v141
	ds_read_b128 v[144:147], v156
	ds_read_b128 v[148:151], v156 offset:1024
	ds_read_b128 v[152:155], v156 offset:2048
	ds_read_b128 v[156:159], v156 offset:3072
	ds_read_b128 v[160:163], v182
	ds_read_b128 v[164:167], v182 offset:1024
	ds_read_b128 v[168:171], v182 offset:2048
	ds_read_b128 v[182:185], v182 offset:3072
	s_add_u32 s4, s4, 0x40000
	s_addc_u32 s5, s5, 0
	s_mov_b32 m0, s31
	v_lshl_add_u64 v[234:235], s[4:5], 0, v[132:133]
	ds_read_b128 v[186:189], v143 offset:32768
	ds_read_b128 v[190:193], v143 offset:33792
	ds_read_b128 v[194:197], v143 offset:34816
	ds_read_b128 v[198:201], v143 offset:35840
	ds_read_b128 v[214:217], v143 offset:36864
	ds_read_b128 v[218:221], v143 offset:37888
	ds_read_b128 v[222:225], v143 offset:38912
	ds_read_b128 v[226:229], v143 offset:39936
	global_load_lds_dwordx4 v[234:235], off
	v_lshl_add_u64 v[234:235], s[4:5], 0, v[130:131]
	s_mov_b32 m0, s35
	s_nop 0
	global_load_lds_dwordx4 v[234:235], off
	s_waitcnt vmcnt(8)
	s_waitcnt lgkmcnt(0)
	s_barrier
	s_waitcnt lgkmcnt(0)
	v_mfma_f32_16x16x32_bf16 v[124:127], v[144:147], v[186:189], v[124:127]
	v_mfma_f32_16x16x32_bf16 v[120:123], v[152:155], v[186:189], v[120:123]
	v_mfma_f32_16x16x32_bf16 v[112:115], v[144:147], v[194:197], v[112:115]
	v_mfma_f32_16x16x32_bf16 v[104:107], v[152:155], v[194:197], v[104:107]
	v_mfma_f32_16x16x32_bf16 v[96:99], v[144:147], v[214:217], v[96:99]
	v_mfma_f32_16x16x32_bf16 v[88:91], v[152:155], v[214:217], v[88:91]
	v_mfma_f32_16x16x32_bf16 v[80:83], v[144:147], v[222:225], v[80:83]
	v_mfma_f32_16x16x32_bf16 v[72:75], v[152:155], v[222:225], v[72:75]
	v_mfma_f32_16x16x32_bf16 v[124:127], v[148:151], v[190:193], v[124:127]
	v_mfma_f32_16x16x32_bf16 v[120:123], v[156:159], v[190:193], v[120:123]
	v_mfma_f32_16x16x32_bf16 v[112:115], v[148:151], v[198:201], v[112:115]
	v_mfma_f32_16x16x32_bf16 v[104:107], v[156:159], v[198:201], v[104:107]
	v_mfma_f32_16x16x32_bf16 v[96:99], v[148:151], v[218:221], v[96:99]
	v_mfma_f32_16x16x32_bf16 v[88:91], v[156:159], v[218:221], v[88:91]
	v_mfma_f32_16x16x32_bf16 v[80:83], v[148:151], v[226:229], v[80:83]
	v_mfma_f32_16x16x32_bf16 v[72:75], v[156:159], v[226:229], v[72:75]
	v_mfma_f32_16x16x32_bf16 v[116:119], v[160:163], v[186:189], v[116:119]
	v_mfma_f32_16x16x32_bf16 v[108:111], v[168:171], v[186:189], v[108:111]
	v_mfma_f32_16x16x32_bf16 v[100:103], v[160:163], v[194:197], v[100:103]
	v_mfma_f32_16x16x32_bf16 v[92:95], v[168:171], v[194:197], v[92:95]
	v_mfma_f32_16x16x32_bf16 v[84:87], v[160:163], v[214:217], v[84:87]
	v_mfma_f32_16x16x32_bf16 v[76:79], v[168:171], v[214:217], v[76:79]
	v_mfma_f32_16x16x32_bf16 v[68:71], v[160:163], v[222:225], v[68:71]
	v_mfma_f32_16x16x32_bf16 v[64:67], v[168:171], v[222:225], v[64:67]
	v_mfma_f32_16x16x32_bf16 v[116:119], v[164:167], v[190:193], v[116:119]
	v_mfma_f32_16x16x32_bf16 v[108:111], v[182:185], v[190:193], v[108:111]
	v_mfma_f32_16x16x32_bf16 v[100:103], v[164:167], v[198:201], v[100:103]
	v_mfma_f32_16x16x32_bf16 v[92:95], v[182:185], v[198:201], v[92:95]
	v_mfma_f32_16x16x32_bf16 v[84:87], v[164:167], v[218:221], v[84:87]
	v_mfma_f32_16x16x32_bf16 v[76:79], v[182:185], v[218:221], v[76:79]
	v_mfma_f32_16x16x32_bf16 v[68:71], v[164:167], v[226:229], v[68:71]
	v_mfma_f32_16x16x32_bf16 v[64:67], v[182:185], v[226:229], v[64:67]
	s_barrier
	s_add_i32 s4, s62, s11
	v_lshl_add_u64 v[138:139], v[138:139], 0, s[36:37]
	s_mov_b32 m0, s4
	ds_read_b128 v[186:189], v143 offset:49152
	ds_read_b128 v[190:193], v143 offset:50176
	ds_read_b128 v[194:197], v143 offset:51200
	ds_read_b128 v[198:201], v143 offset:52224
	ds_read_b128 v[214:217], v143 offset:53248
	ds_read_b128 v[218:221], v143 offset:54272
	ds_read_b128 v[222:225], v143 offset:55296
	ds_read_b128 v[226:229], v143 offset:56320
	global_load_lds_dwordx4 v[138:139], off
	s_add_i32 m0, s4, 0x2000
	s_add_u32 s4, s46, 0x40080
	v_lshl_add_u64 v[138:139], v[202:203], 0, s[36:37]
	s_addc_u32 s5, s47, 0
	s_add_i32 s46, s63, s11
	global_load_lds_dwordx4 v[138:139], off
	v_lshl_add_u64 v[138:139], s[4:5], 0, v[172:173]
	s_mov_b32 m0, s46
	s_nop 0
	global_load_lds_dwordx4 v[138:139], off
	v_lshl_add_u64 v[138:139], s[4:5], 0, v[128:129]
	s_add_i32 m0, s46, 0x2000
	s_nop 0
	global_load_lds_dwordx4 v[138:139], off
	v_lshl_add_u64 v[138:139], v[230:231], 0, s[36:37]
	s_mov_b32 m0, s48
	s_nop 0
	global_load_lds_dwordx4 v[138:139], off
	v_lshl_add_u64 v[138:139], v[232:233], 0, s[36:37]
	s_mov_b32 m0, s49
	s_nop 0
	global_load_lds_dwordx4 v[138:139], off
	s_waitcnt vmcnt(8)
	s_waitcnt lgkmcnt(0)
	s_barrier
	s_waitcnt lgkmcnt(0)
	v_mfma_f32_16x16x32_bf16 v[60:63], v[144:147], v[186:189], v[60:63]
	v_mfma_f32_16x16x32_bf16 v[56:59], v[152:155], v[186:189], v[56:59]
	v_mfma_f32_16x16x32_bf16 v[48:51], v[144:147], v[194:197], v[48:51]
	v_mfma_f32_16x16x32_bf16 v[40:43], v[152:155], v[194:197], v[40:43]
	v_mfma_f32_16x16x32_bf16 v[32:35], v[144:147], v[214:217], v[32:35]
	v_mfma_f32_16x16x32_bf16 v[24:27], v[152:155], v[214:217], v[24:27]
	v_mfma_f32_16x16x32_bf16 v[16:19], v[144:147], v[222:225], v[16:19]
	v_mfma_f32_16x16x32_bf16 v[8:11], v[152:155], v[222:225], v[8:11]
	v_mfma_f32_16x16x32_bf16 v[60:63], v[148:151], v[190:193], v[60:63]
	v_mfma_f32_16x16x32_bf16 v[56:59], v[156:159], v[190:193], v[56:59]
	v_mfma_f32_16x16x32_bf16 v[48:51], v[148:151], v[198:201], v[48:51]
	v_mfma_f32_16x16x32_bf16 v[40:43], v[156:159], v[198:201], v[40:43]
	v_mfma_f32_16x16x32_bf16 v[32:35], v[148:151], v[218:221], v[32:35]
	v_mfma_f32_16x16x32_bf16 v[24:27], v[156:159], v[218:221], v[24:27]
	v_mfma_f32_16x16x32_bf16 v[16:19], v[148:151], v[226:229], v[16:19]
	v_mfma_f32_16x16x32_bf16 v[8:11], v[156:159], v[226:229], v[8:11]
	v_mfma_f32_16x16x32_bf16 v[52:55], v[160:163], v[186:189], v[52:55]
	v_mfma_f32_16x16x32_bf16 v[44:47], v[168:171], v[186:189], v[44:47]
	v_mfma_f32_16x16x32_bf16 v[36:39], v[160:163], v[194:197], v[36:39]
	v_mfma_f32_16x16x32_bf16 v[28:31], v[168:171], v[194:197], v[28:31]
	v_mfma_f32_16x16x32_bf16 v[20:23], v[160:163], v[214:217], v[20:23]
	v_mfma_f32_16x16x32_bf16 v[12:15], v[168:171], v[214:217], v[12:15]
	v_mfma_f32_16x16x32_bf16 v[4:7], v[160:163], v[222:225], v[4:7]
	v_mfma_f32_16x16x32_bf16 v[0:3], v[168:171], v[222:225], v[0:3]
	v_mfma_f32_16x16x32_bf16 v[52:55], v[164:167], v[190:193], v[52:55]
	v_mfma_f32_16x16x32_bf16 v[44:47], v[182:185], v[190:193], v[44:47]
	v_mfma_f32_16x16x32_bf16 v[36:39], v[164:167], v[198:201], v[36:39]
	v_mfma_f32_16x16x32_bf16 v[28:31], v[182:185], v[198:201], v[28:31]
	v_mfma_f32_16x16x32_bf16 v[20:23], v[164:167], v[218:221], v[20:23]
	v_mfma_f32_16x16x32_bf16 v[12:15], v[182:185], v[218:221], v[12:15]
	v_mfma_f32_16x16x32_bf16 v[4:7], v[164:167], v[226:229], v[4:7]
	v_mfma_f32_16x16x32_bf16 v[0:3], v[182:185], v[226:229], v[0:3]
	s_barrier
	s_add_i32 s61, s61, 2
	s_add_u32 s44, s44, 0x100
	s_addc_u32 s45, s45, 0
	s_add_u32 s8, s8, 0x100
	s_addc_u32 s9, s9, 0
	s_cmp_gt_u32 s61, 13
	s_cbranch_scc0 .LBB0_247
	s_and_b64 vcc, exec, s[28:29]
	s_cbranch_vccz .LBB0_250
	s_barrier

.LBB0_914:
	s_add_u32 s4, s56, 0xfffc0080
	s_addc_u32 s5, s57, -1
	s_add_i32 s71, 0, 0x10000
	s_cmp_eq_u32 s70, 12
	s_cselect_b32 s5, s45, s5
	s_cselect_b32 s4, s68, s4
	s_cselect_b32 s59, s39, s9
	s_cselect_b32 s58, s69, s8
	s_add_i32 s74, 0, 0x14000
	v_add_u32_e32 v132, s71, v215
	v_add_u32_e32 v156, s74, v215
	ds_read_b128 v[120:123], v132
	ds_read_b128 v[124:127], v132 offset:1024
	ds_read_b128 v[128:131], v132 offset:2048
	ds_read_b128 v[132:135], v132 offset:3072
	ds_read_b128 v[144:147], v156
	ds_read_b128 v[148:151], v156 offset:1024
	ds_read_b128 v[152:155], v156 offset:2048
	ds_read_b128 v[156:159], v156 offset:3072
	v_lshl_add_u64 v[226:227], s[56:57], 0, v[188:189]
	s_add_i32 m0, s51, 0xc000
	ds_read_b128 v[160:163], v217
	ds_read_b128 v[164:167], v217 offset:1024
	ds_read_b128 v[168:171], v217 offset:2048
	ds_read_b128 v[192:195], v217 offset:3072
	ds_read_b128 v[196:199], v217 offset:4096
	ds_read_b128 v[200:203], v217 offset:5120
	ds_read_b128 v[218:221], v217 offset:6144
	ds_read_b128 v[222:225], v217 offset:7168
	global_load_lds_dwordx4 v[226:227], off
	v_lshl_add_u64 v[226:227], s[56:57], 0, v[190:191]
	s_add_i32 m0, s51, 0xe000
	s_nop 0
	global_load_lds_dwordx4 v[226:227], off
	s_waitcnt vmcnt(8)
	s_waitcnt lgkmcnt(0)
	s_barrier
	s_waitcnt lgkmcnt(0)
	v_mfma_f32_16x16x32_bf16 v[140:143], v[120:123], v[160:163], v[140:143]
	v_mfma_f32_16x16x32_bf16 v[136:139], v[128:131], v[160:163], v[136:139]
	v_mfma_f32_16x16x32_bf16 v[108:111], v[120:123], v[168:171], v[108:111]
	v_mfma_f32_16x16x32_bf16 v[104:107], v[128:131], v[168:171], v[104:107]
	v_mfma_f32_16x16x32_bf16 v[96:99], v[120:123], v[196:199], v[96:99]
	v_mfma_f32_16x16x32_bf16 v[88:91], v[128:131], v[196:199], v[88:91]
	v_mfma_f32_16x16x32_bf16 v[80:83], v[120:123], v[218:221], v[80:83]
	v_mfma_f32_16x16x32_bf16 v[72:75], v[128:131], v[218:221], v[72:75]
	v_mfma_f32_16x16x32_bf16 v[140:143], v[124:127], v[164:167], v[140:143]
	v_mfma_f32_16x16x32_bf16 v[136:139], v[132:135], v[164:167], v[136:139]
	v_mfma_f32_16x16x32_bf16 v[108:111], v[124:127], v[192:195], v[108:111]
	v_mfma_f32_16x16x32_bf16 v[104:107], v[132:135], v[192:195], v[104:107]
	v_mfma_f32_16x16x32_bf16 v[96:99], v[124:127], v[200:203], v[96:99]
	v_mfma_f32_16x16x32_bf16 v[88:91], v[132:135], v[200:203], v[88:91]
	v_mfma_f32_16x16x32_bf16 v[80:83], v[124:127], v[222:225], v[80:83]
	v_mfma_f32_16x16x32_bf16 v[72:75], v[132:135], v[222:225], v[72:75]
	v_mfma_f32_16x16x32_bf16 v[116:119], v[144:147], v[160:163], v[116:119]
	v_mfma_f32_16x16x32_bf16 v[112:115], v[152:155], v[160:163], v[112:115]
	v_mfma_f32_16x16x32_bf16 v[100:103], v[144:147], v[168:171], v[100:103]
	v_mfma_f32_16x16x32_bf16 v[92:95], v[152:155], v[168:171], v[92:95]
	v_mfma_f32_16x16x32_bf16 v[84:87], v[144:147], v[196:199], v[84:87]
	v_mfma_f32_16x16x32_bf16 v[76:79], v[152:155], v[196:199], v[76:79]
	v_mfma_f32_16x16x32_bf16 v[68:71], v[144:147], v[218:221], v[68:71]
	v_mfma_f32_16x16x32_bf16 v[64:67], v[152:155], v[218:221], v[64:67]
	v_mfma_f32_16x16x32_bf16 v[116:119], v[148:151], v[164:167], v[116:119]
	v_mfma_f32_16x16x32_bf16 v[112:115], v[156:159], v[164:167], v[112:115]
	v_mfma_f32_16x16x32_bf16 v[100:103], v[148:151], v[192:195], v[100:103]
	v_mfma_f32_16x16x32_bf16 v[92:95], v[156:159], v[192:195], v[92:95]
	v_mfma_f32_16x16x32_bf16 v[84:87], v[148:151], v[200:203], v[84:87]
	v_mfma_f32_16x16x32_bf16 v[76:79], v[156:159], v[200:203], v[76:79]
	v_mfma_f32_16x16x32_bf16 v[68:71], v[148:151], v[222:225], v[68:71]
	v_mfma_f32_16x16x32_bf16 v[64:67], v[156:159], v[222:225], v[64:67]
	s_barrier
	s_add_i32 s71, s71, s31
	v_lshl_add_u64 v[226:227], s[58:59], 0, v[172:173]
	s_mov_b32 m0, s71
	ds_read_b128 v[160:163], v217 offset:16384
	ds_read_b128 v[164:167], v217 offset:17408
	ds_read_b128 v[168:171], v217 offset:18432
	ds_read_b128 v[192:195], v217 offset:19456
	ds_read_b128 v[196:199], v217 offset:20480
	ds_read_b128 v[200:203], v217 offset:21504
	ds_read_b128 v[218:221], v217 offset:22528
	ds_read_b128 v[222:225], v217 offset:23552
	global_load_lds_dwordx4 v[226:227], off
	s_add_i32 m0, s71, 0x2000
	s_add_u32 s72, s58, 0x40000
	v_lshl_add_u64 v[228:229], s[58:59], 0, v[182:183]
	s_addc_u32 s73, s59, 0
	s_add_i32 s71, s74, s31
	global_load_lds_dwordx4 v[228:229], off
	v_lshl_add_u64 v[230:231], s[72:73], 0, v[172:173]
	s_mov_b32 m0, s71
	v_lshl_add_u64 v[232:233], s[4:5], 0, v[184:185]
	global_load_lds_dwordx4 v[230:231], off
	v_lshl_add_u64 v[230:231], s[72:73], 0, v[182:183]
	s_add_i32 m0, s71, 0x2000
	s_nop 0
	global_load_lds_dwordx4 v[230:231], off
	v_lshl_add_u64 v[230:231], s[4:5], 0, v[186:187]
	s_mov_b32 m0, s51
	s_nop 0
	global_load_lds_dwordx4 v[230:231], off
	s_mov_b32 m0, s60
	s_nop 0
	global_load_lds_dwordx4 v[232:233], off
	s_waitcnt vmcnt(8)
	s_waitcnt lgkmcnt(0)
	s_barrier
	s_waitcnt lgkmcnt(0)
	v_mfma_f32_16x16x32_bf16 v[60:63], v[120:123], v[160:163], v[60:63]
	v_mfma_f32_16x16x32_bf16 v[56:59], v[128:131], v[160:163], v[56:59]
	v_mfma_f32_16x16x32_bf16 v[48:51], v[120:123], v[168:171], v[48:51]
	v_mfma_f32_16x16x32_bf16 v[40:43], v[128:131], v[168:171], v[40:43]
	v_mfma_f32_16x16x32_bf16 v[32:35], v[120:123], v[196:199], v[32:35]
	v_mfma_f32_16x16x32_bf16 v[24:27], v[128:131], v[196:199], v[24:27]
	v_mfma_f32_16x16x32_bf16 v[16:19], v[120:123], v[218:221], v[16:19]
	v_mfma_f32_16x16x32_bf16 v[8:11], v[128:131], v[218:221], v[8:11]
	v_mfma_f32_16x16x32_bf16 v[60:63], v[124:127], v[164:167], v[60:63]
	v_mfma_f32_16x16x32_bf16 v[56:59], v[132:135], v[164:167], v[56:59]
	v_mfma_f32_16x16x32_bf16 v[48:51], v[124:127], v[192:195], v[48:51]
	v_mfma_f32_16x16x32_bf16 v[40:43], v[132:135], v[192:195], v[40:43]
	v_mfma_f32_16x16x32_bf16 v[32:35], v[124:127], v[200:203], v[32:35]
	v_mfma_f32_16x16x32_bf16 v[24:27], v[132:135], v[200:203], v[24:27]
	v_mfma_f32_16x16x32_bf16 v[16:19], v[124:127], v[222:225], v[16:19]
	v_mfma_f32_16x16x32_bf16 v[8:11], v[132:135], v[222:225], v[8:11]
	v_mfma_f32_16x16x32_bf16 v[52:55], v[144:147], v[160:163], v[52:55]
	v_mfma_f32_16x16x32_bf16 v[44:47], v[152:155], v[160:163], v[44:47]
	v_mfma_f32_16x16x32_bf16 v[36:39], v[144:147], v[168:171], v[36:39]
	v_mfma_f32_16x16x32_bf16 v[28:31], v[152:155], v[168:171], v[28:31]
	v_mfma_f32_16x16x32_bf16 v[20:23], v[144:147], v[196:199], v[20:23]
	v_mfma_f32_16x16x32_bf16 v[12:15], v[152:155], v[196:199], v[12:15]
	v_mfma_f32_16x16x32_bf16 v[4:7], v[144:147], v[218:221], v[4:7]
	v_mfma_f32_16x16x32_bf16 v[0:3], v[152:155], v[218:221], v[0:3]
	v_mfma_f32_16x16x32_bf16 v[52:55], v[148:151], v[164:167], v[52:55]
	v_mfma_f32_16x16x32_bf16 v[44:47], v[156:159], v[164:167], v[44:47]
	v_mfma_f32_16x16x32_bf16 v[36:39], v[148:151], v[192:195], v[36:39]
	v_mfma_f32_16x16x32_bf16 v[28:31], v[156:159], v[192:195], v[28:31]
	v_mfma_f32_16x16x32_bf16 v[20:23], v[148:151], v[200:203], v[20:23]
	v_mfma_f32_16x16x32_bf16 v[12:15], v[156:159], v[200:203], v[12:15]
	v_mfma_f32_16x16x32_bf16 v[4:7], v[148:151], v[222:225], v[4:7]
	v_mfma_f32_16x16x32_bf16 v[0:3], v[156:159], v[222:225], v[0:3]
	s_barrier
	s_add_i32 s71, 0, 0x18000
	s_add_i32 s72, 0, 0x1c000
	v_add_u32_e32 v132, s71, v215
	v_add_u32_e32 v156, s72, v215
	ds_read_b128 v[120:123], v132
	ds_read_b128 v[124:127], v132 offset:1024
	ds_read_b128 v[128:131], v132 offset:2048
	ds_read_b128 v[132:135], v132 offset:3072
	ds_read_b128 v[144:147], v156
	ds_read_b128 v[148:151], v156 offset:1024
	ds_read_b128 v[152:155], v156 offset:2048
	ds_read_b128 v[156:159], v156 offset:3072
	s_add_u32 s4, s4, 0x40000
	s_addc_u32 s5, s5, 0
	s_mov_b32 m0, s61
	v_lshl_add_u64 v[234:235], s[4:5], 0, v[186:187]
	ds_read_b128 v[160:163], v217 offset:32768
	ds_read_b128 v[164:167], v217 offset:33792
	ds_read_b128 v[168:171], v217 offset:34816
	ds_read_b128 v[192:195], v217 offset:35840
	ds_read_b128 v[196:199], v217 offset:36864
	ds_read_b128 v[200:203], v217 offset:37888
	ds_read_b128 v[218:221], v217 offset:38912
	ds_read_b128 v[222:225], v217 offset:39936
	global_load_lds_dwordx4 v[234:235], off
	v_lshl_add_u64 v[234:235], s[4:5], 0, v[184:185]
	s_mov_b32 m0, s62
	s_nop 0
	global_load_lds_dwordx4 v[234:235], off
	s_waitcnt vmcnt(8)
	s_waitcnt lgkmcnt(0)
	s_barrier
	s_waitcnt lgkmcnt(0)
	v_mfma_f32_16x16x32_bf16 v[140:143], v[120:123], v[160:163], v[140:143]
	v_mfma_f32_16x16x32_bf16 v[136:139], v[128:131], v[160:163], v[136:139]
	v_mfma_f32_16x16x32_bf16 v[108:111], v[120:123], v[168:171], v[108:111]
	v_mfma_f32_16x16x32_bf16 v[104:107], v[128:131], v[168:171], v[104:107]
	v_mfma_f32_16x16x32_bf16 v[96:99], v[120:123], v[196:199], v[96:99]
	v_mfma_f32_16x16x32_bf16 v[88:91], v[128:131], v[196:199], v[88:91]
	v_mfma_f32_16x16x32_bf16 v[80:83], v[120:123], v[218:221], v[80:83]
	v_mfma_f32_16x16x32_bf16 v[72:75], v[128:131], v[218:221], v[72:75]
	v_mfma_f32_16x16x32_bf16 v[140:143], v[124:127], v[164:167], v[140:143]
	v_mfma_f32_16x16x32_bf16 v[136:139], v[132:135], v[164:167], v[136:139]
	v_mfma_f32_16x16x32_bf16 v[108:111], v[124:127], v[192:195], v[108:111]
	v_mfma_f32_16x16x32_bf16 v[104:107], v[132:135], v[192:195], v[104:107]
	v_mfma_f32_16x16x32_bf16 v[96:99], v[124:127], v[200:203], v[96:99]
	v_mfma_f32_16x16x32_bf16 v[88:91], v[132:135], v[200:203], v[88:91]
	v_mfma_f32_16x16x32_bf16 v[80:83], v[124:127], v[222:225], v[80:83]
	v_mfma_f32_16x16x32_bf16 v[72:75], v[132:135], v[222:225], v[72:75]
	v_mfma_f32_16x16x32_bf16 v[116:119], v[144:147], v[160:163], v[116:119]
	v_mfma_f32_16x16x32_bf16 v[112:115], v[152:155], v[160:163], v[112:115]
	v_mfma_f32_16x16x32_bf16 v[100:103], v[144:147], v[168:171], v[100:103]
	v_mfma_f32_16x16x32_bf16 v[92:95], v[152:155], v[168:171], v[92:95]
	v_mfma_f32_16x16x32_bf16 v[84:87], v[144:147], v[196:199], v[84:87]
	v_mfma_f32_16x16x32_bf16 v[76:79], v[152:155], v[196:199], v[76:79]
	v_mfma_f32_16x16x32_bf16 v[68:71], v[144:147], v[218:221], v[68:71]
	v_mfma_f32_16x16x32_bf16 v[64:67], v[152:155], v[218:221], v[64:67]
	v_mfma_f32_16x16x32_bf16 v[116:119], v[148:151], v[164:167], v[116:119]
	v_mfma_f32_16x16x32_bf16 v[112:115], v[156:159], v[164:167], v[112:115]
	v_mfma_f32_16x16x32_bf16 v[100:103], v[148:151], v[192:195], v[100:103]
	v_mfma_f32_16x16x32_bf16 v[92:95], v[156:159], v[192:195], v[92:95]
	v_mfma_f32_16x16x32_bf16 v[84:87], v[148:151], v[200:203], v[84:87]
	v_mfma_f32_16x16x32_bf16 v[76:79], v[156:159], v[200:203], v[76:79]
	v_mfma_f32_16x16x32_bf16 v[68:71], v[148:151], v[222:225], v[68:71]
	v_mfma_f32_16x16x32_bf16 v[64:67], v[156:159], v[222:225], v[64:67]
	s_barrier
	s_add_i32 s4, s71, s31
	v_lshl_add_u64 v[226:227], v[226:227], 0, s[36:37]
	s_mov_b32 m0, s4
	ds_read_b128 v[160:163], v217 offset:49152
	ds_read_b128 v[164:167], v217 offset:50176
	ds_read_b128 v[168:171], v217 offset:51200
	ds_read_b128 v[192:195], v217 offset:52224
	ds_read_b128 v[196:199], v217 offset:53248
	ds_read_b128 v[200:203], v217 offset:54272
	ds_read_b128 v[218:221], v217 offset:55296
	ds_read_b128 v[222:225], v217 offset:56320
	global_load_lds_dwordx4 v[226:227], off
	s_add_i32 m0, s4, 0x2000
	s_add_u32 s4, s58, 0x40080
	v_lshl_add_u64 v[226:227], v[228:229], 0, s[36:37]
	s_addc_u32 s5, s59, 0
	s_add_i32 s58, s72, s31
	global_load_lds_dwordx4 v[226:227], off
	v_lshl_add_u64 v[226:227], s[4:5], 0, v[172:173]
	s_mov_b32 m0, s58
	s_nop 0
	global_load_lds_dwordx4 v[226:227], off
	v_lshl_add_u64 v[226:227], s[4:5], 0, v[182:183]
	s_add_i32 m0, s58, 0x2000
	s_nop 0
	global_load_lds_dwordx4 v[226:227], off
	v_lshl_add_u64 v[226:227], v[230:231], 0, s[36:37]
	s_mov_b32 m0, s63
	s_nop 0
	global_load_lds_dwordx4 v[226:227], off
	v_lshl_add_u64 v[226:227], v[232:233], 0, s[36:37]
	s_mov_b32 m0, s64
	s_nop 0
	global_load_lds_dwordx4 v[226:227], off
	s_waitcnt vmcnt(8)
	s_waitcnt lgkmcnt(0)
	s_barrier
	s_waitcnt lgkmcnt(0)
	v_mfma_f32_16x16x32_bf16 v[60:63], v[120:123], v[160:163], v[60:63]
	v_mfma_f32_16x16x32_bf16 v[56:59], v[128:131], v[160:163], v[56:59]
	v_mfma_f32_16x16x32_bf16 v[48:51], v[120:123], v[168:171], v[48:51]
	v_mfma_f32_16x16x32_bf16 v[40:43], v[128:131], v[168:171], v[40:43]
	v_mfma_f32_16x16x32_bf16 v[32:35], v[120:123], v[196:199], v[32:35]
	v_mfma_f32_16x16x32_bf16 v[24:27], v[128:131], v[196:199], v[24:27]
	v_mfma_f32_16x16x32_bf16 v[16:19], v[120:123], v[218:221], v[16:19]
	v_mfma_f32_16x16x32_bf16 v[8:11], v[128:131], v[218:221], v[8:11]
	v_mfma_f32_16x16x32_bf16 v[60:63], v[124:127], v[164:167], v[60:63]
	v_mfma_f32_16x16x32_bf16 v[56:59], v[132:135], v[164:167], v[56:59]
	v_mfma_f32_16x16x32_bf16 v[48:51], v[124:127], v[192:195], v[48:51]
	v_mfma_f32_16x16x32_bf16 v[40:43], v[132:135], v[192:195], v[40:43]
	v_mfma_f32_16x16x32_bf16 v[32:35], v[124:127], v[200:203], v[32:35]
	v_mfma_f32_16x16x32_bf16 v[24:27], v[132:135], v[200:203], v[24:27]
	v_mfma_f32_16x16x32_bf16 v[16:19], v[124:127], v[222:225], v[16:19]
	v_mfma_f32_16x16x32_bf16 v[8:11], v[132:135], v[222:225], v[8:11]
	v_mfma_f32_16x16x32_bf16 v[52:55], v[144:147], v[160:163], v[52:55]
	v_mfma_f32_16x16x32_bf16 v[44:47], v[152:155], v[160:163], v[44:47]
	v_mfma_f32_16x16x32_bf16 v[36:39], v[144:147], v[168:171], v[36:39]
	v_mfma_f32_16x16x32_bf16 v[28:31], v[152:155], v[168:171], v[28:31]
	v_mfma_f32_16x16x32_bf16 v[20:23], v[144:147], v[196:199], v[20:23]
	v_mfma_f32_16x16x32_bf16 v[12:15], v[152:155], v[196:199], v[12:15]
	v_mfma_f32_16x16x32_bf16 v[4:7], v[144:147], v[218:221], v[4:7]
	v_mfma_f32_16x16x32_bf16 v[0:3], v[152:155], v[218:221], v[0:3]
	v_mfma_f32_16x16x32_bf16 v[52:55], v[148:151], v[164:167], v[52:55]
	v_mfma_f32_16x16x32_bf16 v[44:47], v[156:159], v[164:167], v[44:47]
	v_mfma_f32_16x16x32_bf16 v[36:39], v[148:151], v[192:195], v[36:39]
	v_mfma_f32_16x16x32_bf16 v[28:31], v[156:159], v[192:195], v[28:31]
	v_mfma_f32_16x16x32_bf16 v[20:23], v[148:151], v[200:203], v[20:23]
	v_mfma_f32_16x16x32_bf16 v[12:15], v[156:159], v[200:203], v[12:15]
	v_mfma_f32_16x16x32_bf16 v[4:7], v[148:151], v[222:225], v[4:7]
	v_mfma_f32_16x16x32_bf16 v[0:3], v[156:159], v[222:225], v[0:3]
	s_barrier
	s_add_i32 s70, s70, 2
	s_add_u32 s56, s56, 0x100
	s_addc_u32 s57, s57, 0
	s_add_u32 s8, s8, 0x100
	s_addc_u32 s9, s9, 0
	s_cmp_gt_u32 s70, 13
	s_cbranch_scc0 .LBB0_914
	s_and_b64 vcc, exec, s[28:29]
	s_cbranch_vccz .LBB0_917
	s_barrier

.LBB0_934:
	s_add_u32 s4, s48, 0xfffc0080
	s_addc_u32 s5, s49, -1
	s_add_i32 s69, 0, 0x10000
	s_cmp_eq_u32 s68, 12
	s_cselect_b32 s5, s45, s5
	s_cselect_b32 s4, s66, s4
	s_cselect_b32 s57, s43, s9
	s_cselect_b32 s56, s67, s8
	s_add_i32 s72, 0, 0x14000
	v_add_u32_e32 v76, s69, v159
	v_add_u32_e32 v170, s72, v159
	ds_read_b128 v[64:67], v76
	ds_read_b128 v[68:71], v76 offset:1024
	ds_read_b128 v[72:75], v76 offset:2048
	ds_read_b128 v[76:79], v76 offset:3072
	ds_read_b128 v[154:157], v170
	ds_read_b128 v[162:165], v170 offset:1024
	ds_read_b128 v[166:169], v170 offset:2048
	ds_read_b128 v[182:185], v170 offset:3072
	v_lshl_add_u64 v[170:171], s[48:49], 0, v[150:151]
	s_add_i32 m0, s58, 0xc000
	ds_read_b128 v[186:189], v161
	ds_read_b128 v[190:193], v161 offset:1024
	ds_read_b128 v[194:197], v161 offset:2048
	ds_read_b128 v[198:201], v161 offset:3072
	ds_read_b128 v[214:217], v161 offset:4096
	ds_read_b128 v[218:221], v161 offset:5120
	ds_read_b128 v[222:225], v161 offset:6144
	ds_read_b128 v[226:229], v161 offset:7168
	global_load_lds_dwordx4 v[170:171], off
	v_lshl_add_u64 v[170:171], s[48:49], 0, v[152:153]
	s_add_i32 m0, s58, 0xe000
	s_nop 0
	global_load_lds_dwordx4 v[170:171], off
	s_waitcnt vmcnt(8)
	s_waitcnt lgkmcnt(0)
	s_barrier
	s_waitcnt lgkmcnt(0)
	v_mfma_f32_16x16x32_bf16 v[140:143], v[64:67], v[186:189], v[140:143]
	v_mfma_f32_16x16x32_bf16 v[136:139], v[72:75], v[186:189], v[136:139]
	v_mfma_f32_16x16x32_bf16 v[132:135], v[64:67], v[194:197], v[132:135]
	v_mfma_f32_16x16x32_bf16 v[128:131], v[72:75], v[194:197], v[128:131]
	v_mfma_f32_16x16x32_bf16 v[108:111], v[64:67], v[214:217], v[108:111]
	v_mfma_f32_16x16x32_bf16 v[104:107], v[72:75], v[214:217], v[104:107]
	v_mfma_f32_16x16x32_bf16 v[100:103], v[64:67], v[222:225], v[100:103]
	v_mfma_f32_16x16x32_bf16 v[96:99], v[72:75], v[222:225], v[96:99]
	v_mfma_f32_16x16x32_bf16 v[140:143], v[68:71], v[190:193], v[140:143]
	v_mfma_f32_16x16x32_bf16 v[136:139], v[76:79], v[190:193], v[136:139]
	v_mfma_f32_16x16x32_bf16 v[132:135], v[68:71], v[198:201], v[132:135]
	v_mfma_f32_16x16x32_bf16 v[128:131], v[76:79], v[198:201], v[128:131]
	v_mfma_f32_16x16x32_bf16 v[108:111], v[68:71], v[218:221], v[108:111]
	v_mfma_f32_16x16x32_bf16 v[104:107], v[76:79], v[218:221], v[104:107]
	v_mfma_f32_16x16x32_bf16 v[100:103], v[68:71], v[226:229], v[100:103]
	v_mfma_f32_16x16x32_bf16 v[96:99], v[76:79], v[226:229], v[96:99]
	v_mfma_f32_16x16x32_bf16 v[124:127], v[154:157], v[186:189], v[124:127]
	v_mfma_f32_16x16x32_bf16 v[120:123], v[166:169], v[186:189], v[120:123]
	v_mfma_f32_16x16x32_bf16 v[116:119], v[154:157], v[194:197], v[116:119]
	v_mfma_f32_16x16x32_bf16 v[112:115], v[166:169], v[194:197], v[112:115]
	v_mfma_f32_16x16x32_bf16 v[92:95], v[154:157], v[214:217], v[92:95]
	v_mfma_f32_16x16x32_bf16 v[88:91], v[166:169], v[214:217], v[88:91]
	v_mfma_f32_16x16x32_bf16 v[84:87], v[154:157], v[222:225], v[84:87]
	v_mfma_f32_16x16x32_bf16 v[80:83], v[166:169], v[222:225], v[80:83]
	v_mfma_f32_16x16x32_bf16 v[124:127], v[162:165], v[190:193], v[124:127]
	v_mfma_f32_16x16x32_bf16 v[120:123], v[182:185], v[190:193], v[120:123]
	v_mfma_f32_16x16x32_bf16 v[116:119], v[162:165], v[198:201], v[116:119]
	v_mfma_f32_16x16x32_bf16 v[112:115], v[182:185], v[198:201], v[112:115]
	v_mfma_f32_16x16x32_bf16 v[92:95], v[162:165], v[218:221], v[92:95]
	v_mfma_f32_16x16x32_bf16 v[88:91], v[182:185], v[218:221], v[88:91]
	v_mfma_f32_16x16x32_bf16 v[84:87], v[162:165], v[226:229], v[84:87]
	v_mfma_f32_16x16x32_bf16 v[80:83], v[182:185], v[226:229], v[80:83]
	s_barrier
	s_add_i32 s69, s69, s51
	v_lshl_add_u64 v[170:171], s[56:57], 0, v[172:173]
	s_mov_b32 m0, s69
	ds_read_b128 v[186:189], v161 offset:16384
	ds_read_b128 v[190:193], v161 offset:17408
	ds_read_b128 v[194:197], v161 offset:18432
	ds_read_b128 v[198:201], v161 offset:19456
	ds_read_b128 v[214:217], v161 offset:20480
	ds_read_b128 v[218:221], v161 offset:21504
	ds_read_b128 v[222:225], v161 offset:22528
	ds_read_b128 v[226:229], v161 offset:23552
	global_load_lds_dwordx4 v[170:171], off
	s_add_i32 m0, s69, 0x2000
	s_add_u32 s70, s56, 0x40000
	v_lshl_add_u64 v[202:203], s[56:57], 0, v[144:145]
	s_addc_u32 s71, s57, 0
	s_add_i32 s69, s72, s51
	global_load_lds_dwordx4 v[202:203], off
	v_lshl_add_u64 v[230:231], s[70:71], 0, v[172:173]
	s_mov_b32 m0, s69
	v_lshl_add_u64 v[232:233], s[4:5], 0, v[146:147]
	global_load_lds_dwordx4 v[230:231], off
	v_lshl_add_u64 v[230:231], s[70:71], 0, v[144:145]
	s_add_i32 m0, s69, 0x2000
	s_nop 0
	global_load_lds_dwordx4 v[230:231], off
	v_lshl_add_u64 v[230:231], s[4:5], 0, v[148:149]
	s_mov_b32 m0, s58
	s_nop 0
	global_load_lds_dwordx4 v[230:231], off
	s_mov_b32 m0, s59
	s_nop 0
	global_load_lds_dwordx4 v[232:233], off
	s_waitcnt vmcnt(8)
	s_waitcnt lgkmcnt(0)
	s_barrier
	s_waitcnt lgkmcnt(0)
	v_mfma_f32_16x16x32_bf16 v[60:63], v[64:67], v[186:189], v[60:63]
	v_mfma_f32_16x16x32_bf16 v[56:59], v[72:75], v[186:189], v[56:59]
	v_mfma_f32_16x16x32_bf16 v[52:55], v[64:67], v[194:197], v[52:55]
	v_mfma_f32_16x16x32_bf16 v[48:51], v[72:75], v[194:197], v[48:51]
	v_mfma_f32_16x16x32_bf16 v[28:31], v[64:67], v[214:217], v[28:31]
	v_mfma_f32_16x16x32_bf16 v[24:27], v[72:75], v[214:217], v[24:27]
	v_mfma_f32_16x16x32_bf16 v[20:23], v[64:67], v[222:225], v[20:23]
	v_mfma_f32_16x16x32_bf16 v[16:19], v[72:75], v[222:225], v[16:19]
	v_mfma_f32_16x16x32_bf16 v[60:63], v[68:71], v[190:193], v[60:63]
	v_mfma_f32_16x16x32_bf16 v[56:59], v[76:79], v[190:193], v[56:59]
	v_mfma_f32_16x16x32_bf16 v[52:55], v[68:71], v[198:201], v[52:55]
	v_mfma_f32_16x16x32_bf16 v[48:51], v[76:79], v[198:201], v[48:51]
	v_mfma_f32_16x16x32_bf16 v[28:31], v[68:71], v[218:221], v[28:31]
	v_mfma_f32_16x16x32_bf16 v[24:27], v[76:79], v[218:221], v[24:27]
	v_mfma_f32_16x16x32_bf16 v[20:23], v[68:71], v[226:229], v[20:23]
	v_mfma_f32_16x16x32_bf16 v[16:19], v[76:79], v[226:229], v[16:19]
	v_mfma_f32_16x16x32_bf16 v[44:47], v[154:157], v[186:189], v[44:47]
	v_mfma_f32_16x16x32_bf16 v[40:43], v[166:169], v[186:189], v[40:43]
	v_mfma_f32_16x16x32_bf16 v[36:39], v[154:157], v[194:197], v[36:39]
	v_mfma_f32_16x16x32_bf16 v[32:35], v[166:169], v[194:197], v[32:35]
	v_mfma_f32_16x16x32_bf16 v[12:15], v[154:157], v[214:217], v[12:15]
	v_mfma_f32_16x16x32_bf16 v[8:11], v[166:169], v[214:217], v[8:11]
	v_mfma_f32_16x16x32_bf16 v[4:7], v[154:157], v[222:225], v[4:7]
	v_mfma_f32_16x16x32_bf16 v[0:3], v[166:169], v[222:225], v[0:3]
	v_mfma_f32_16x16x32_bf16 v[44:47], v[162:165], v[190:193], v[44:47]
	v_mfma_f32_16x16x32_bf16 v[40:43], v[182:185], v[190:193], v[40:43]
	v_mfma_f32_16x16x32_bf16 v[36:39], v[162:165], v[198:201], v[36:39]
	v_mfma_f32_16x16x32_bf16 v[32:35], v[182:185], v[198:201], v[32:35]
	v_mfma_f32_16x16x32_bf16 v[12:15], v[162:165], v[218:221], v[12:15]
	v_mfma_f32_16x16x32_bf16 v[8:11], v[182:185], v[218:221], v[8:11]
	v_mfma_f32_16x16x32_bf16 v[4:7], v[162:165], v[226:229], v[4:7]
	v_mfma_f32_16x16x32_bf16 v[0:3], v[182:185], v[226:229], v[0:3]
	s_barrier
	s_add_i32 s69, 0, 0x18000
	s_add_i32 s70, 0, 0x1c000
	v_add_u32_e32 v76, s69, v159
	v_add_u32_e32 v182, s70, v159
	ds_read_b128 v[64:67], v76
	ds_read_b128 v[68:71], v76 offset:1024
	ds_read_b128 v[72:75], v76 offset:2048
	ds_read_b128 v[76:79], v76 offset:3072
	ds_read_b128 v[154:157], v182
	ds_read_b128 v[162:165], v182 offset:1024
	ds_read_b128 v[166:169], v182 offset:2048
	ds_read_b128 v[182:185], v182 offset:3072
	s_add_u32 s4, s4, 0x40000
	s_addc_u32 s5, s5, 0
	s_mov_b32 m0, s60
	v_lshl_add_u64 v[234:235], s[4:5], 0, v[148:149]
	ds_read_b128 v[186:189], v161 offset:32768
	ds_read_b128 v[190:193], v161 offset:33792
	ds_read_b128 v[194:197], v161 offset:34816
	ds_read_b128 v[198:201], v161 offset:35840
	ds_read_b128 v[214:217], v161 offset:36864
	ds_read_b128 v[218:221], v161 offset:37888
	ds_read_b128 v[222:225], v161 offset:38912
	ds_read_b128 v[226:229], v161 offset:39936
	global_load_lds_dwordx4 v[234:235], off
	v_lshl_add_u64 v[234:235], s[4:5], 0, v[146:147]
	s_mov_b32 m0, s61
	s_nop 0
	global_load_lds_dwordx4 v[234:235], off
	s_waitcnt vmcnt(8)
	s_waitcnt lgkmcnt(0)
	s_barrier
	s_waitcnt lgkmcnt(0)
	v_mfma_f32_16x16x32_bf16 v[140:143], v[64:67], v[186:189], v[140:143]
	v_mfma_f32_16x16x32_bf16 v[136:139], v[72:75], v[186:189], v[136:139]
	v_mfma_f32_16x16x32_bf16 v[132:135], v[64:67], v[194:197], v[132:135]
	v_mfma_f32_16x16x32_bf16 v[128:131], v[72:75], v[194:197], v[128:131]
	v_mfma_f32_16x16x32_bf16 v[108:111], v[64:67], v[214:217], v[108:111]
	v_mfma_f32_16x16x32_bf16 v[104:107], v[72:75], v[214:217], v[104:107]
	v_mfma_f32_16x16x32_bf16 v[100:103], v[64:67], v[222:225], v[100:103]
	v_mfma_f32_16x16x32_bf16 v[96:99], v[72:75], v[222:225], v[96:99]
	v_mfma_f32_16x16x32_bf16 v[140:143], v[68:71], v[190:193], v[140:143]
	v_mfma_f32_16x16x32_bf16 v[136:139], v[76:79], v[190:193], v[136:139]
	v_mfma_f32_16x16x32_bf16 v[132:135], v[68:71], v[198:201], v[132:135]
	v_mfma_f32_16x16x32_bf16 v[128:131], v[76:79], v[198:201], v[128:131]
	v_mfma_f32_16x16x32_bf16 v[108:111], v[68:71], v[218:221], v[108:111]
	v_mfma_f32_16x16x32_bf16 v[104:107], v[76:79], v[218:221], v[104:107]
	v_mfma_f32_16x16x32_bf16 v[100:103], v[68:71], v[226:229], v[100:103]
	v_mfma_f32_16x16x32_bf16 v[96:99], v[76:79], v[226:229], v[96:99]
	v_mfma_f32_16x16x32_bf16 v[124:127], v[154:157], v[186:189], v[124:127]
	v_mfma_f32_16x16x32_bf16 v[120:123], v[166:169], v[186:189], v[120:123]
	v_mfma_f32_16x16x32_bf16 v[116:119], v[154:157], v[194:197], v[116:119]
	v_mfma_f32_16x16x32_bf16 v[112:115], v[166:169], v[194:197], v[112:115]
	v_mfma_f32_16x16x32_bf16 v[92:95], v[154:157], v[214:217], v[92:95]
	v_mfma_f32_16x16x32_bf16 v[88:91], v[166:169], v[214:217], v[88:91]
	v_mfma_f32_16x16x32_bf16 v[84:87], v[154:157], v[222:225], v[84:87]
	v_mfma_f32_16x16x32_bf16 v[80:83], v[166:169], v[222:225], v[80:83]
	v_mfma_f32_16x16x32_bf16 v[124:127], v[162:165], v[190:193], v[124:127]
	v_mfma_f32_16x16x32_bf16 v[120:123], v[182:185], v[190:193], v[120:123]
	v_mfma_f32_16x16x32_bf16 v[116:119], v[162:165], v[198:201], v[116:119]
	v_mfma_f32_16x16x32_bf16 v[112:115], v[182:185], v[198:201], v[112:115]
	v_mfma_f32_16x16x32_bf16 v[92:95], v[162:165], v[218:221], v[92:95]
	v_mfma_f32_16x16x32_bf16 v[88:91], v[182:185], v[218:221], v[88:91]
	v_mfma_f32_16x16x32_bf16 v[84:87], v[162:165], v[226:229], v[84:87]
	v_mfma_f32_16x16x32_bf16 v[80:83], v[182:185], v[226:229], v[80:83]
	s_barrier
	s_add_i32 s4, s69, s51
	v_lshl_add_u64 v[170:171], v[170:171], 0, s[36:37]
	s_mov_b32 m0, s4
	ds_read_b128 v[186:189], v161 offset:49152
	ds_read_b128 v[190:193], v161 offset:50176
	ds_read_b128 v[194:197], v161 offset:51200
	ds_read_b128 v[198:201], v161 offset:52224
	ds_read_b128 v[214:217], v161 offset:53248
	ds_read_b128 v[218:221], v161 offset:54272
	ds_read_b128 v[222:225], v161 offset:55296
	ds_read_b128 v[226:229], v161 offset:56320
	global_load_lds_dwordx4 v[170:171], off
	s_add_i32 m0, s4, 0x2000
	s_add_u32 s4, s56, 0x40080
	v_lshl_add_u64 v[170:171], v[202:203], 0, s[36:37]
	s_addc_u32 s5, s57, 0
	s_add_i32 s56, s70, s51
	global_load_lds_dwordx4 v[170:171], off
	v_lshl_add_u64 v[170:171], s[4:5], 0, v[172:173]
	s_mov_b32 m0, s56
	s_nop 0
	global_load_lds_dwordx4 v[170:171], off
	v_lshl_add_u64 v[170:171], s[4:5], 0, v[144:145]
	s_add_i32 m0, s56, 0x2000
	s_nop 0
	global_load_lds_dwordx4 v[170:171], off
	v_lshl_add_u64 v[170:171], v[230:231], 0, s[36:37]
	s_mov_b32 m0, s62
	s_nop 0
	global_load_lds_dwordx4 v[170:171], off
	v_lshl_add_u64 v[170:171], v[232:233], 0, s[36:37]
	s_mov_b32 m0, s63
	s_nop 0
	global_load_lds_dwordx4 v[170:171], off
	s_waitcnt vmcnt(8)
	s_waitcnt lgkmcnt(0)
	s_barrier
	s_waitcnt lgkmcnt(0)
	v_mfma_f32_16x16x32_bf16 v[60:63], v[64:67], v[186:189], v[60:63]
	v_mfma_f32_16x16x32_bf16 v[56:59], v[72:75], v[186:189], v[56:59]
	v_mfma_f32_16x16x32_bf16 v[52:55], v[64:67], v[194:197], v[52:55]
	v_mfma_f32_16x16x32_bf16 v[48:51], v[72:75], v[194:197], v[48:51]
	v_mfma_f32_16x16x32_bf16 v[28:31], v[64:67], v[214:217], v[28:31]
	v_mfma_f32_16x16x32_bf16 v[24:27], v[72:75], v[214:217], v[24:27]
	v_mfma_f32_16x16x32_bf16 v[20:23], v[64:67], v[222:225], v[20:23]
	v_mfma_f32_16x16x32_bf16 v[16:19], v[72:75], v[222:225], v[16:19]
	v_mfma_f32_16x16x32_bf16 v[60:63], v[68:71], v[190:193], v[60:63]
	v_mfma_f32_16x16x32_bf16 v[56:59], v[76:79], v[190:193], v[56:59]
	v_mfma_f32_16x16x32_bf16 v[52:55], v[68:71], v[198:201], v[52:55]
	v_mfma_f32_16x16x32_bf16 v[48:51], v[76:79], v[198:201], v[48:51]
	v_mfma_f32_16x16x32_bf16 v[28:31], v[68:71], v[218:221], v[28:31]
	v_mfma_f32_16x16x32_bf16 v[24:27], v[76:79], v[218:221], v[24:27]
	v_mfma_f32_16x16x32_bf16 v[20:23], v[68:71], v[226:229], v[20:23]
	v_mfma_f32_16x16x32_bf16 v[16:19], v[76:79], v[226:229], v[16:19]
	v_mfma_f32_16x16x32_bf16 v[44:47], v[154:157], v[186:189], v[44:47]
	v_mfma_f32_16x16x32_bf16 v[40:43], v[166:169], v[186:189], v[40:43]
	v_mfma_f32_16x16x32_bf16 v[36:39], v[154:157], v[194:197], v[36:39]
	v_mfma_f32_16x16x32_bf16 v[32:35], v[166:169], v[194:197], v[32:35]
	v_mfma_f32_16x16x32_bf16 v[12:15], v[154:157], v[214:217], v[12:15]
	v_mfma_f32_16x16x32_bf16 v[8:11], v[166:169], v[214:217], v[8:11]
	v_mfma_f32_16x16x32_bf16 v[4:7], v[154:157], v[222:225], v[4:7]
	v_mfma_f32_16x16x32_bf16 v[0:3], v[166:169], v[222:225], v[0:3]
	v_mfma_f32_16x16x32_bf16 v[44:47], v[162:165], v[190:193], v[44:47]
	v_mfma_f32_16x16x32_bf16 v[40:43], v[182:185], v[190:193], v[40:43]
	v_mfma_f32_16x16x32_bf16 v[36:39], v[162:165], v[198:201], v[36:39]
	v_mfma_f32_16x16x32_bf16 v[32:35], v[182:185], v[198:201], v[32:35]
	v_mfma_f32_16x16x32_bf16 v[12:15], v[162:165], v[218:221], v[12:15]
	v_mfma_f32_16x16x32_bf16 v[8:11], v[182:185], v[218:221], v[8:11]
	v_mfma_f32_16x16x32_bf16 v[4:7], v[162:165], v[226:229], v[4:7]
	v_mfma_f32_16x16x32_bf16 v[0:3], v[182:185], v[226:229], v[0:3]
	s_barrier
	s_add_i32 s68, s68, 2
	s_add_u32 s48, s48, 0x100
	s_addc_u32 s49, s49, 0
	s_add_u32 s8, s8, 0x100
	s_addc_u32 s9, s9, 0
	s_cmp_gt_u32 s68, 13
	s_cbranch_scc0 .LBB0_934
	s_and_b64 vcc, exec, s[38:39]
	s_cbranch_vccz .LBB0_937
	s_barrier

.LBB0_1154:
	s_add_u32 s4, s56, 0xfffc0080
	s_addc_u32 s5, s57, -1
	s_add_i32 s75, 0, 0x10000
	s_cmp_eq_u32 s74, 12
	s_cselect_b32 s5, s47, s5
	s_cselect_b32 s4, s70, s4
	v_add_u32_e32 v138, s75, v141
	s_cselect_b32 s59, s45, s73
	s_cselect_b32 s58, s71, s72
	s_add_i32 s77, 0, 0x14000
	ds_read_b128 v[144:147], v138
	ds_read_b128 v[148:151], v138 offset:1024
	ds_read_b128 v[152:155], v138 offset:2048
	ds_read_b128 v[156:159], v138 offset:3072
	v_add_u32_e32 v138, s77, v141
	ds_read_b128 v[160:163], v138
	ds_read_b128 v[164:167], v138 offset:1024
	ds_read_b128 v[168:171], v138 offset:2048
	ds_read_b128 v[182:185], v138 offset:3072
	v_lshl_add_u64 v[138:139], s[56:57], 0, v[134:135]
	s_add_i32 m0, s51, 0xc000
	ds_read_b128 v[186:189], v143
	ds_read_b128 v[190:193], v143 offset:1024
	ds_read_b128 v[194:197], v143 offset:2048
	ds_read_b128 v[198:201], v143 offset:3072
	ds_read_b128 v[214:217], v143 offset:4096
	ds_read_b128 v[218:221], v143 offset:5120
	ds_read_b128 v[222:225], v143 offset:6144
	ds_read_b128 v[226:229], v143 offset:7168
	global_load_lds_dwordx4 v[138:139], off
	v_lshl_add_u64 v[138:139], s[56:57], 0, v[136:137]
	s_add_i32 m0, s51, 0xe000
	s_nop 0
	global_load_lds_dwordx4 v[138:139], off
	s_waitcnt vmcnt(8)
	s_waitcnt lgkmcnt(0)
	s_barrier
	s_waitcnt lgkmcnt(0)
	v_mfma_f32_16x16x32_bf16 v[124:127], v[144:147], v[186:189], v[124:127]
	v_mfma_f32_16x16x32_bf16 v[120:123], v[152:155], v[186:189], v[120:123]
	v_mfma_f32_16x16x32_bf16 v[116:119], v[144:147], v[194:197], v[116:119]
	v_mfma_f32_16x16x32_bf16 v[108:111], v[152:155], v[194:197], v[108:111]
	v_mfma_f32_16x16x32_bf16 v[100:103], v[144:147], v[214:217], v[100:103]
	v_mfma_f32_16x16x32_bf16 v[92:95], v[152:155], v[214:217], v[92:95]
	v_mfma_f32_16x16x32_bf16 v[84:87], v[144:147], v[222:225], v[84:87]
	v_mfma_f32_16x16x32_bf16 v[76:79], v[152:155], v[222:225], v[76:79]
	v_mfma_f32_16x16x32_bf16 v[124:127], v[148:151], v[190:193], v[124:127]
	v_mfma_f32_16x16x32_bf16 v[120:123], v[156:159], v[190:193], v[120:123]
	v_mfma_f32_16x16x32_bf16 v[116:119], v[148:151], v[198:201], v[116:119]
	v_mfma_f32_16x16x32_bf16 v[108:111], v[156:159], v[198:201], v[108:111]
	v_mfma_f32_16x16x32_bf16 v[100:103], v[148:151], v[218:221], v[100:103]
	v_mfma_f32_16x16x32_bf16 v[92:95], v[156:159], v[218:221], v[92:95]
	v_mfma_f32_16x16x32_bf16 v[84:87], v[148:151], v[226:229], v[84:87]
	v_mfma_f32_16x16x32_bf16 v[76:79], v[156:159], v[226:229], v[76:79]
	v_mfma_f32_16x16x32_bf16 v[112:115], v[160:163], v[186:189], v[112:115]
	v_mfma_f32_16x16x32_bf16 v[104:107], v[168:171], v[186:189], v[104:107]
	v_mfma_f32_16x16x32_bf16 v[96:99], v[160:163], v[194:197], v[96:99]
	v_mfma_f32_16x16x32_bf16 v[88:91], v[168:171], v[194:197], v[88:91]
	v_mfma_f32_16x16x32_bf16 v[80:83], v[160:163], v[214:217], v[80:83]
	v_mfma_f32_16x16x32_bf16 v[72:75], v[168:171], v[214:217], v[72:75]
	v_mfma_f32_16x16x32_bf16 v[68:71], v[160:163], v[222:225], v[68:71]
	v_mfma_f32_16x16x32_bf16 v[64:67], v[168:171], v[222:225], v[64:67]
	v_mfma_f32_16x16x32_bf16 v[112:115], v[164:167], v[190:193], v[112:115]
	v_mfma_f32_16x16x32_bf16 v[104:107], v[182:185], v[190:193], v[104:107]
	v_mfma_f32_16x16x32_bf16 v[96:99], v[164:167], v[198:201], v[96:99]
	v_mfma_f32_16x16x32_bf16 v[88:91], v[182:185], v[198:201], v[88:91]
	v_mfma_f32_16x16x32_bf16 v[80:83], v[164:167], v[218:221], v[80:83]
	v_mfma_f32_16x16x32_bf16 v[72:75], v[182:185], v[218:221], v[72:75]
	v_mfma_f32_16x16x32_bf16 v[68:71], v[164:167], v[226:229], v[68:71]
	v_mfma_f32_16x16x32_bf16 v[64:67], v[182:185], v[226:229], v[64:67]
	s_barrier
	s_add_i32 s75, s75, s63
	v_lshl_add_u64 v[138:139], s[58:59], 0, v[172:173]
	s_mov_b32 m0, s75
	ds_read_b128 v[186:189], v143 offset:16384
	ds_read_b128 v[190:193], v143 offset:17408
	ds_read_b128 v[194:197], v143 offset:18432
	ds_read_b128 v[198:201], v143 offset:19456
	ds_read_b128 v[214:217], v143 offset:20480
	ds_read_b128 v[218:221], v143 offset:21504
	ds_read_b128 v[222:225], v143 offset:22528
	ds_read_b128 v[226:229], v143 offset:23552
	global_load_lds_dwordx4 v[138:139], off
	s_add_i32 m0, s75, 0x2000
	s_add_u32 s78, s58, 0x40000
	v_lshl_add_u64 v[202:203], s[58:59], 0, v[128:129]
	s_addc_u32 s79, s59, 0
	s_add_i32 s75, s77, s63
	global_load_lds_dwordx4 v[202:203], off
	v_lshl_add_u64 v[230:231], s[78:79], 0, v[172:173]
	s_mov_b32 m0, s75
	v_lshl_add_u64 v[232:233], s[4:5], 0, v[130:131]
	global_load_lds_dwordx4 v[230:231], off
	v_lshl_add_u64 v[230:231], s[78:79], 0, v[128:129]
	s_add_i32 m0, s75, 0x2000
	s_nop 0
	global_load_lds_dwordx4 v[230:231], off
	v_lshl_add_u64 v[230:231], s[4:5], 0, v[132:133]
	s_mov_b32 m0, s51
	s_nop 0
	global_load_lds_dwordx4 v[230:231], off
	s_mov_b32 m0, s53
	s_nop 0
	global_load_lds_dwordx4 v[232:233], off
	s_waitcnt vmcnt(8)
	s_waitcnt lgkmcnt(0)
	s_barrier
	s_waitcnt lgkmcnt(0)
	v_mfma_f32_16x16x32_bf16 v[60:63], v[144:147], v[186:189], v[60:63]
	v_mfma_f32_16x16x32_bf16 v[56:59], v[152:155], v[186:189], v[56:59]
	v_mfma_f32_16x16x32_bf16 v[52:55], v[144:147], v[194:197], v[52:55]
	v_mfma_f32_16x16x32_bf16 v[44:47], v[152:155], v[194:197], v[44:47]
	v_mfma_f32_16x16x32_bf16 v[36:39], v[144:147], v[214:217], v[36:39]
	v_mfma_f32_16x16x32_bf16 v[28:31], v[152:155], v[214:217], v[28:31]
	v_mfma_f32_16x16x32_bf16 v[20:23], v[144:147], v[222:225], v[20:23]
	v_mfma_f32_16x16x32_bf16 v[12:15], v[152:155], v[222:225], v[12:15]
	v_mfma_f32_16x16x32_bf16 v[60:63], v[148:151], v[190:193], v[60:63]
	v_mfma_f32_16x16x32_bf16 v[56:59], v[156:159], v[190:193], v[56:59]
	v_mfma_f32_16x16x32_bf16 v[52:55], v[148:151], v[198:201], v[52:55]
	v_mfma_f32_16x16x32_bf16 v[44:47], v[156:159], v[198:201], v[44:47]
	v_mfma_f32_16x16x32_bf16 v[36:39], v[148:151], v[218:221], v[36:39]
	v_mfma_f32_16x16x32_bf16 v[28:31], v[156:159], v[218:221], v[28:31]
	v_mfma_f32_16x16x32_bf16 v[20:23], v[148:151], v[226:229], v[20:23]
	v_mfma_f32_16x16x32_bf16 v[12:15], v[156:159], v[226:229], v[12:15]
	v_mfma_f32_16x16x32_bf16 v[48:51], v[160:163], v[186:189], v[48:51]
	v_mfma_f32_16x16x32_bf16 v[40:43], v[168:171], v[186:189], v[40:43]
	v_mfma_f32_16x16x32_bf16 v[32:35], v[160:163], v[194:197], v[32:35]
	v_mfma_f32_16x16x32_bf16 v[24:27], v[168:171], v[194:197], v[24:27]
	v_mfma_f32_16x16x32_bf16 v[16:19], v[160:163], v[214:217], v[16:19]
	v_mfma_f32_16x16x32_bf16 v[8:11], v[168:171], v[214:217], v[8:11]
	v_mfma_f32_16x16x32_bf16 v[4:7], v[160:163], v[222:225], v[4:7]
	v_mfma_f32_16x16x32_bf16 v[0:3], v[168:171], v[222:225], v[0:3]
	v_mfma_f32_16x16x32_bf16 v[48:51], v[164:167], v[190:193], v[48:51]
	v_mfma_f32_16x16x32_bf16 v[40:43], v[182:185], v[190:193], v[40:43]
	v_mfma_f32_16x16x32_bf16 v[32:35], v[164:167], v[198:201], v[32:35]
	v_mfma_f32_16x16x32_bf16 v[24:27], v[182:185], v[198:201], v[24:27]
	v_mfma_f32_16x16x32_bf16 v[16:19], v[164:167], v[218:221], v[16:19]
	v_mfma_f32_16x16x32_bf16 v[8:11], v[182:185], v[218:221], v[8:11]
	v_mfma_f32_16x16x32_bf16 v[4:7], v[164:167], v[226:229], v[4:7]
	v_mfma_f32_16x16x32_bf16 v[0:3], v[182:185], v[226:229], v[0:3]
	s_barrier
	s_add_i32 s75, 0, 0x18000
	s_add_i32 s77, 0, 0x1c000
	v_add_u32_e32 v156, s75, v141
	v_add_u32_e32 v182, s77, v141
	ds_read_b128 v[144:147], v156
	ds_read_b128 v[148:151], v156 offset:1024
	ds_read_b128 v[152:155], v156 offset:2048
	ds_read_b128 v[156:159], v156 offset:3072
	ds_read_b128 v[160:163], v182
	ds_read_b128 v[164:167], v182 offset:1024
	ds_read_b128 v[168:171], v182 offset:2048
	ds_read_b128 v[182:185], v182 offset:3072
	s_add_u32 s4, s4, 0x40000
	s_addc_u32 s5, s5, 0
	s_mov_b32 m0, s65
	v_lshl_add_u64 v[234:235], s[4:5], 0, v[132:133]
	ds_read_b128 v[186:189], v143 offset:32768
	ds_read_b128 v[190:193], v143 offset:33792
	ds_read_b128 v[194:197], v143 offset:34816
	ds_read_b128 v[198:201], v143 offset:35840
	ds_read_b128 v[214:217], v143 offset:36864
	ds_read_b128 v[218:221], v143 offset:37888
	ds_read_b128 v[222:225], v143 offset:38912
	ds_read_b128 v[226:229], v143 offset:39936
	global_load_lds_dwordx4 v[234:235], off
	v_lshl_add_u64 v[234:235], s[4:5], 0, v[130:131]
	s_mov_b32 m0, s66
	s_nop 0
	global_load_lds_dwordx4 v[234:235], off
	s_waitcnt vmcnt(8)
	s_waitcnt lgkmcnt(0)
	s_barrier
	s_waitcnt lgkmcnt(0)
	v_mfma_f32_16x16x32_bf16 v[124:127], v[144:147], v[186:189], v[124:127]
	v_mfma_f32_16x16x32_bf16 v[120:123], v[152:155], v[186:189], v[120:123]
	v_mfma_f32_16x16x32_bf16 v[116:119], v[144:147], v[194:197], v[116:119]
	v_mfma_f32_16x16x32_bf16 v[108:111], v[152:155], v[194:197], v[108:111]
	v_mfma_f32_16x16x32_bf16 v[100:103], v[144:147], v[214:217], v[100:103]
	v_mfma_f32_16x16x32_bf16 v[92:95], v[152:155], v[214:217], v[92:95]
	v_mfma_f32_16x16x32_bf16 v[84:87], v[144:147], v[222:225], v[84:87]
	v_mfma_f32_16x16x32_bf16 v[76:79], v[152:155], v[222:225], v[76:79]
	v_mfma_f32_16x16x32_bf16 v[124:127], v[148:151], v[190:193], v[124:127]
	v_mfma_f32_16x16x32_bf16 v[120:123], v[156:159], v[190:193], v[120:123]
	v_mfma_f32_16x16x32_bf16 v[116:119], v[148:151], v[198:201], v[116:119]
	v_mfma_f32_16x16x32_bf16 v[108:111], v[156:159], v[198:201], v[108:111]
	v_mfma_f32_16x16x32_bf16 v[100:103], v[148:151], v[218:221], v[100:103]
	v_mfma_f32_16x16x32_bf16 v[92:95], v[156:159], v[218:221], v[92:95]
	v_mfma_f32_16x16x32_bf16 v[84:87], v[148:151], v[226:229], v[84:87]
	v_mfma_f32_16x16x32_bf16 v[76:79], v[156:159], v[226:229], v[76:79]
	v_mfma_f32_16x16x32_bf16 v[112:115], v[160:163], v[186:189], v[112:115]
	v_mfma_f32_16x16x32_bf16 v[104:107], v[168:171], v[186:189], v[104:107]
	v_mfma_f32_16x16x32_bf16 v[96:99], v[160:163], v[194:197], v[96:99]
	v_mfma_f32_16x16x32_bf16 v[88:91], v[168:171], v[194:197], v[88:91]
	v_mfma_f32_16x16x32_bf16 v[80:83], v[160:163], v[214:217], v[80:83]
	v_mfma_f32_16x16x32_bf16 v[72:75], v[168:171], v[214:217], v[72:75]
	v_mfma_f32_16x16x32_bf16 v[68:71], v[160:163], v[222:225], v[68:71]
	v_mfma_f32_16x16x32_bf16 v[64:67], v[168:171], v[222:225], v[64:67]
	v_mfma_f32_16x16x32_bf16 v[112:115], v[164:167], v[190:193], v[112:115]
	v_mfma_f32_16x16x32_bf16 v[104:107], v[182:185], v[190:193], v[104:107]
	v_mfma_f32_16x16x32_bf16 v[96:99], v[164:167], v[198:201], v[96:99]
	v_mfma_f32_16x16x32_bf16 v[88:91], v[182:185], v[198:201], v[88:91]
	v_mfma_f32_16x16x32_bf16 v[80:83], v[164:167], v[218:221], v[80:83]
	v_mfma_f32_16x16x32_bf16 v[72:75], v[182:185], v[218:221], v[72:75]
	v_mfma_f32_16x16x32_bf16 v[68:71], v[164:167], v[226:229], v[68:71]
	v_mfma_f32_16x16x32_bf16 v[64:67], v[182:185], v[226:229], v[64:67]
	s_barrier
	s_add_i32 s4, s75, s63
	v_lshl_add_u64 v[138:139], v[138:139], 0, s[36:37]
	s_mov_b32 m0, s4
	ds_read_b128 v[186:189], v143 offset:49152
	ds_read_b128 v[190:193], v143 offset:50176
	ds_read_b128 v[194:197], v143 offset:51200
	ds_read_b128 v[198:201], v143 offset:52224
	ds_read_b128 v[214:217], v143 offset:53248
	ds_read_b128 v[218:221], v143 offset:54272
	ds_read_b128 v[222:225], v143 offset:55296
	ds_read_b128 v[226:229], v143 offset:56320
	global_load_lds_dwordx4 v[138:139], off
	s_add_i32 m0, s4, 0x2000
	s_add_u32 s4, s58, 0x40080
	v_lshl_add_u64 v[138:139], v[202:203], 0, s[36:37]
	s_addc_u32 s5, s59, 0
	s_add_i32 s58, s77, s63
	global_load_lds_dwordx4 v[138:139], off
	v_lshl_add_u64 v[138:139], s[4:5], 0, v[172:173]
	s_mov_b32 m0, s58
	s_nop 0
	global_load_lds_dwordx4 v[138:139], off
	v_lshl_add_u64 v[138:139], s[4:5], 0, v[128:129]
	s_add_i32 m0, s58, 0x2000
	s_nop 0
	global_load_lds_dwordx4 v[138:139], off
	v_lshl_add_u64 v[138:139], v[230:231], 0, s[36:37]
	s_mov_b32 m0, s67
	s_nop 0
	global_load_lds_dwordx4 v[138:139], off
	v_lshl_add_u64 v[138:139], v[232:233], 0, s[36:37]
	s_mov_b32 m0, s68
	s_nop 0
	global_load_lds_dwordx4 v[138:139], off
	s_waitcnt vmcnt(8)
	s_waitcnt lgkmcnt(0)
	s_barrier
	s_waitcnt lgkmcnt(0)
	v_mfma_f32_16x16x32_bf16 v[60:63], v[144:147], v[186:189], v[60:63]
	v_mfma_f32_16x16x32_bf16 v[56:59], v[152:155], v[186:189], v[56:59]
	v_mfma_f32_16x16x32_bf16 v[52:55], v[144:147], v[194:197], v[52:55]
	v_mfma_f32_16x16x32_bf16 v[44:47], v[152:155], v[194:197], v[44:47]
	v_mfma_f32_16x16x32_bf16 v[36:39], v[144:147], v[214:217], v[36:39]
	v_mfma_f32_16x16x32_bf16 v[28:31], v[152:155], v[214:217], v[28:31]
	v_mfma_f32_16x16x32_bf16 v[20:23], v[144:147], v[222:225], v[20:23]
	v_mfma_f32_16x16x32_bf16 v[12:15], v[152:155], v[222:225], v[12:15]
	v_mfma_f32_16x16x32_bf16 v[60:63], v[148:151], v[190:193], v[60:63]
	v_mfma_f32_16x16x32_bf16 v[56:59], v[156:159], v[190:193], v[56:59]
	v_mfma_f32_16x16x32_bf16 v[52:55], v[148:151], v[198:201], v[52:55]
	v_mfma_f32_16x16x32_bf16 v[44:47], v[156:159], v[198:201], v[44:47]
	v_mfma_f32_16x16x32_bf16 v[36:39], v[148:151], v[218:221], v[36:39]
	v_mfma_f32_16x16x32_bf16 v[28:31], v[156:159], v[218:221], v[28:31]
	v_mfma_f32_16x16x32_bf16 v[20:23], v[148:151], v[226:229], v[20:23]
	v_mfma_f32_16x16x32_bf16 v[12:15], v[156:159], v[226:229], v[12:15]
	v_mfma_f32_16x16x32_bf16 v[48:51], v[160:163], v[186:189], v[48:51]
	v_mfma_f32_16x16x32_bf16 v[40:43], v[168:171], v[186:189], v[40:43]
	v_mfma_f32_16x16x32_bf16 v[32:35], v[160:163], v[194:197], v[32:35]
	v_mfma_f32_16x16x32_bf16 v[24:27], v[168:171], v[194:197], v[24:27]
	v_mfma_f32_16x16x32_bf16 v[16:19], v[160:163], v[214:217], v[16:19]
	v_mfma_f32_16x16x32_bf16 v[8:11], v[168:171], v[214:217], v[8:11]
	v_mfma_f32_16x16x32_bf16 v[4:7], v[160:163], v[222:225], v[4:7]
	v_mfma_f32_16x16x32_bf16 v[0:3], v[168:171], v[222:225], v[0:3]
	v_mfma_f32_16x16x32_bf16 v[48:51], v[164:167], v[190:193], v[48:51]
	v_mfma_f32_16x16x32_bf16 v[40:43], v[182:185], v[190:193], v[40:43]
	v_mfma_f32_16x16x32_bf16 v[32:35], v[164:167], v[198:201], v[32:35]
	v_mfma_f32_16x16x32_bf16 v[24:27], v[182:185], v[198:201], v[24:27]
	v_mfma_f32_16x16x32_bf16 v[16:19], v[164:167], v[218:221], v[16:19]
	v_mfma_f32_16x16x32_bf16 v[8:11], v[182:185], v[218:221], v[8:11]
	v_mfma_f32_16x16x32_bf16 v[4:7], v[164:167], v[226:229], v[4:7]
	v_mfma_f32_16x16x32_bf16 v[0:3], v[182:185], v[226:229], v[0:3]
	s_barrier
	s_add_i32 s74, s74, 2
	s_add_u32 s56, s56, 0x100
	s_addc_u32 s57, s57, 0
	s_add_u32 s72, s72, 0x100
	s_addc_u32 s73, s73, 0
	s_cmp_gt_u32 s74, 13
	s_cbranch_scc0 .LBB0_1154
	s_and_b64 vcc, exec, s[40:41]
	s_cbranch_vccz .LBB0_1157
	s_barrier

.LBB0_1412:
	s_add_i32 s63, s4, 2
	s_add_u32 s64, s46, 0x80
	s_addc_u32 s5, s47, 0
	s_add_i32 s66, 0, 0x10000
	s_cmp_eq_u32 s55, s4
	s_cselect_b32 s5, s41, s5
	s_cselect_b32 s4, s40, s64
	s_cselect_b32 s65, s45, s49
	s_cselect_b32 s64, s44, s48
	s_add_i32 s67, 0, 0x14000
	v_add_u32_e32 v132, s66, v215
	v_add_u32_e32 v156, s67, v215
	ds_read_b128 v[120:123], v132
	ds_read_b128 v[124:127], v132 offset:1024
	ds_read_b128 v[128:131], v132 offset:2048
	ds_read_b128 v[132:135], v132 offset:3072
	ds_read_b128 v[144:147], v156
	ds_read_b128 v[148:151], v156 offset:1024
	ds_read_b128 v[152:155], v156 offset:2048
	ds_read_b128 v[156:159], v156 offset:3072
	v_lshl_add_u64 v[226:227], s[46:47], 0, v[188:189]
	s_add_i32 m0, s51, 0xc000
	ds_read_b128 v[160:163], v217
	ds_read_b128 v[164:167], v217 offset:1024
	ds_read_b128 v[168:171], v217 offset:2048
	ds_read_b128 v[192:195], v217 offset:3072
	ds_read_b128 v[196:199], v217 offset:4096
	ds_read_b128 v[200:203], v217 offset:5120
	ds_read_b128 v[218:221], v217 offset:6144
	ds_read_b128 v[222:225], v217 offset:7168
	global_load_lds_dwordx4 v[226:227], off
	v_lshl_add_u64 v[226:227], s[46:47], 0, v[190:191]
	s_add_i32 m0, s51, 0xe000
	s_nop 0
	global_load_lds_dwordx4 v[226:227], off
	s_waitcnt vmcnt(8)
	s_waitcnt lgkmcnt(0)
	s_barrier
	s_waitcnt lgkmcnt(0)
	v_mfma_f32_16x16x32_bf16 v[140:143], v[120:123], v[160:163], v[140:143]
	v_mfma_f32_16x16x32_bf16 v[136:139], v[128:131], v[160:163], v[136:139]
	v_mfma_f32_16x16x32_bf16 v[108:111], v[120:123], v[168:171], v[108:111]
	v_mfma_f32_16x16x32_bf16 v[104:107], v[128:131], v[168:171], v[104:107]
	v_mfma_f32_16x16x32_bf16 v[96:99], v[120:123], v[196:199], v[96:99]
	v_mfma_f32_16x16x32_bf16 v[88:91], v[128:131], v[196:199], v[88:91]
	v_mfma_f32_16x16x32_bf16 v[80:83], v[120:123], v[218:221], v[80:83]
	v_mfma_f32_16x16x32_bf16 v[72:75], v[128:131], v[218:221], v[72:75]
	v_mfma_f32_16x16x32_bf16 v[140:143], v[124:127], v[164:167], v[140:143]
	v_mfma_f32_16x16x32_bf16 v[136:139], v[132:135], v[164:167], v[136:139]
	v_mfma_f32_16x16x32_bf16 v[108:111], v[124:127], v[192:195], v[108:111]
	v_mfma_f32_16x16x32_bf16 v[104:107], v[132:135], v[192:195], v[104:107]
	v_mfma_f32_16x16x32_bf16 v[96:99], v[124:127], v[200:203], v[96:99]
	v_mfma_f32_16x16x32_bf16 v[88:91], v[132:135], v[200:203], v[88:91]
	v_mfma_f32_16x16x32_bf16 v[80:83], v[124:127], v[222:225], v[80:83]
	v_mfma_f32_16x16x32_bf16 v[72:75], v[132:135], v[222:225], v[72:75]
	v_mfma_f32_16x16x32_bf16 v[116:119], v[144:147], v[160:163], v[116:119]
	v_mfma_f32_16x16x32_bf16 v[112:115], v[152:155], v[160:163], v[112:115]
	v_mfma_f32_16x16x32_bf16 v[100:103], v[144:147], v[168:171], v[100:103]
	v_mfma_f32_16x16x32_bf16 v[92:95], v[152:155], v[168:171], v[92:95]
	v_mfma_f32_16x16x32_bf16 v[84:87], v[144:147], v[196:199], v[84:87]
	v_mfma_f32_16x16x32_bf16 v[76:79], v[152:155], v[196:199], v[76:79]
	v_mfma_f32_16x16x32_bf16 v[68:71], v[144:147], v[218:221], v[68:71]
	v_mfma_f32_16x16x32_bf16 v[64:67], v[152:155], v[218:221], v[64:67]
	v_mfma_f32_16x16x32_bf16 v[116:119], v[148:151], v[164:167], v[116:119]
	v_mfma_f32_16x16x32_bf16 v[112:115], v[156:159], v[164:167], v[112:115]
	v_mfma_f32_16x16x32_bf16 v[100:103], v[148:151], v[192:195], v[100:103]
	v_mfma_f32_16x16x32_bf16 v[92:95], v[156:159], v[192:195], v[92:95]
	v_mfma_f32_16x16x32_bf16 v[84:87], v[148:151], v[200:203], v[84:87]
	v_mfma_f32_16x16x32_bf16 v[76:79], v[156:159], v[200:203], v[76:79]
	v_mfma_f32_16x16x32_bf16 v[68:71], v[148:151], v[222:225], v[68:71]
	v_mfma_f32_16x16x32_bf16 v[64:67], v[156:159], v[222:225], v[64:67]
	s_barrier
	s_add_i32 s66, s66, s50
	v_lshl_add_u64 v[226:227], s[64:65], 0, v[172:173]
	s_mov_b32 m0, s66
	ds_read_b128 v[160:163], v217 offset:16384
	ds_read_b128 v[164:167], v217 offset:17408
	ds_read_b128 v[168:171], v217 offset:18432
	ds_read_b128 v[192:195], v217 offset:19456
	ds_read_b128 v[196:199], v217 offset:20480
	ds_read_b128 v[200:203], v217 offset:21504
	ds_read_b128 v[218:221], v217 offset:22528
	ds_read_b128 v[222:225], v217 offset:23552
	global_load_lds_dwordx4 v[226:227], off
	s_add_i32 m0, s66, 0x2000
	v_lshl_add_u64 v[228:229], s[64:65], 0, v[182:183]
	s_add_u32 s64, s64, s26
	s_addc_u32 s65, s65, 0
	s_add_i32 s66, s67, s50
	global_load_lds_dwordx4 v[228:229], off
	v_lshl_add_u64 v[230:231], s[64:65], 0, v[172:173]
	s_mov_b32 m0, s66
	v_lshl_add_u64 v[232:233], s[64:65], 0, v[182:183]
	global_load_lds_dwordx4 v[230:231], off
	s_add_i32 m0, s66, 0x2000
	v_lshl_add_u64 v[234:235], s[4:5], 0, v[186:187]
	global_load_lds_dwordx4 v[232:233], off
	s_mov_b32 m0, s51
	v_lshl_add_u64 v[236:237], s[4:5], 0, v[184:185]
	global_load_lds_dwordx4 v[234:235], off
	s_mov_b32 m0, s52
	s_nop 0
	global_load_lds_dwordx4 v[236:237], off
	s_waitcnt vmcnt(8)
	s_waitcnt lgkmcnt(0)
	s_barrier
	s_waitcnt lgkmcnt(0)
	v_mfma_f32_16x16x32_bf16 v[60:63], v[120:123], v[160:163], v[60:63]
	v_mfma_f32_16x16x32_bf16 v[56:59], v[128:131], v[160:163], v[56:59]
	v_mfma_f32_16x16x32_bf16 v[48:51], v[120:123], v[168:171], v[48:51]
	v_mfma_f32_16x16x32_bf16 v[40:43], v[128:131], v[168:171], v[40:43]
	v_mfma_f32_16x16x32_bf16 v[32:35], v[120:123], v[196:199], v[32:35]
	v_mfma_f32_16x16x32_bf16 v[24:27], v[128:131], v[196:199], v[24:27]
	v_mfma_f32_16x16x32_bf16 v[16:19], v[120:123], v[218:221], v[16:19]
	v_mfma_f32_16x16x32_bf16 v[8:11], v[128:131], v[218:221], v[8:11]
	v_mfma_f32_16x16x32_bf16 v[60:63], v[124:127], v[164:167], v[60:63]
	v_mfma_f32_16x16x32_bf16 v[56:59], v[132:135], v[164:167], v[56:59]
	v_mfma_f32_16x16x32_bf16 v[48:51], v[124:127], v[192:195], v[48:51]
	v_mfma_f32_16x16x32_bf16 v[40:43], v[132:135], v[192:195], v[40:43]
	v_mfma_f32_16x16x32_bf16 v[32:35], v[124:127], v[200:203], v[32:35]
	v_mfma_f32_16x16x32_bf16 v[24:27], v[132:135], v[200:203], v[24:27]
	v_mfma_f32_16x16x32_bf16 v[16:19], v[124:127], v[222:225], v[16:19]
	v_mfma_f32_16x16x32_bf16 v[8:11], v[132:135], v[222:225], v[8:11]
	v_mfma_f32_16x16x32_bf16 v[52:55], v[144:147], v[160:163], v[52:55]
	v_mfma_f32_16x16x32_bf16 v[44:47], v[152:155], v[160:163], v[44:47]
	v_mfma_f32_16x16x32_bf16 v[36:39], v[144:147], v[168:171], v[36:39]
	v_mfma_f32_16x16x32_bf16 v[28:31], v[152:155], v[168:171], v[28:31]
	v_mfma_f32_16x16x32_bf16 v[20:23], v[144:147], v[196:199], v[20:23]
	v_mfma_f32_16x16x32_bf16 v[12:15], v[152:155], v[196:199], v[12:15]
	v_mfma_f32_16x16x32_bf16 v[4:7], v[144:147], v[218:221], v[4:7]
	v_mfma_f32_16x16x32_bf16 v[0:3], v[152:155], v[218:221], v[0:3]
	v_mfma_f32_16x16x32_bf16 v[52:55], v[148:151], v[164:167], v[52:55]
	v_mfma_f32_16x16x32_bf16 v[44:47], v[156:159], v[164:167], v[44:47]
	v_mfma_f32_16x16x32_bf16 v[36:39], v[148:151], v[192:195], v[36:39]
	v_mfma_f32_16x16x32_bf16 v[28:31], v[156:159], v[192:195], v[28:31]
	v_mfma_f32_16x16x32_bf16 v[20:23], v[148:151], v[200:203], v[20:23]
	v_mfma_f32_16x16x32_bf16 v[12:15], v[156:159], v[200:203], v[12:15]
	v_mfma_f32_16x16x32_bf16 v[4:7], v[148:151], v[222:225], v[4:7]
	v_mfma_f32_16x16x32_bf16 v[0:3], v[156:159], v[222:225], v[0:3]
	s_barrier
	s_add_i32 s64, 0, 0x18000
	s_add_i32 s65, 0, 0x1c000
	v_add_u32_e32 v132, s64, v215
	v_add_u32_e32 v156, s65, v215
	ds_read_b128 v[120:123], v132
	ds_read_b128 v[124:127], v132 offset:1024
	ds_read_b128 v[128:131], v132 offset:2048
	ds_read_b128 v[132:135], v132 offset:3072
	ds_read_b128 v[144:147], v156
	ds_read_b128 v[148:151], v156 offset:1024
	ds_read_b128 v[152:155], v156 offset:2048
	ds_read_b128 v[156:159], v156 offset:3072
	s_add_u32 s4, s4, s26
	s_addc_u32 s5, s5, 0
	s_mov_b32 m0, s53
	v_lshl_add_u64 v[238:239], s[4:5], 0, v[186:187]
	ds_read_b128 v[160:163], v217 offset:32768
	ds_read_b128 v[164:167], v217 offset:33792
	ds_read_b128 v[168:171], v217 offset:34816
	ds_read_b128 v[192:195], v217 offset:35840
	ds_read_b128 v[196:199], v217 offset:36864
	ds_read_b128 v[200:203], v217 offset:37888
	ds_read_b128 v[218:221], v217 offset:38912
	ds_read_b128 v[222:225], v217 offset:39936
	global_load_lds_dwordx4 v[238:239], off
	v_lshl_add_u64 v[238:239], s[4:5], 0, v[184:185]
	s_mov_b32 m0, s54
	s_nop 0
	global_load_lds_dwordx4 v[238:239], off
	s_waitcnt vmcnt(8)
	s_waitcnt lgkmcnt(0)
	s_barrier
	s_waitcnt lgkmcnt(0)
	v_mfma_f32_16x16x32_bf16 v[140:143], v[120:123], v[160:163], v[140:143]
	v_mfma_f32_16x16x32_bf16 v[136:139], v[128:131], v[160:163], v[136:139]
	v_mfma_f32_16x16x32_bf16 v[108:111], v[120:123], v[168:171], v[108:111]
	v_mfma_f32_16x16x32_bf16 v[104:107], v[128:131], v[168:171], v[104:107]
	v_mfma_f32_16x16x32_bf16 v[96:99], v[120:123], v[196:199], v[96:99]
	v_mfma_f32_16x16x32_bf16 v[88:91], v[128:131], v[196:199], v[88:91]
	v_mfma_f32_16x16x32_bf16 v[80:83], v[120:123], v[218:221], v[80:83]
	v_mfma_f32_16x16x32_bf16 v[72:75], v[128:131], v[218:221], v[72:75]
	v_mfma_f32_16x16x32_bf16 v[140:143], v[124:127], v[164:167], v[140:143]
	v_mfma_f32_16x16x32_bf16 v[136:139], v[132:135], v[164:167], v[136:139]
	v_mfma_f32_16x16x32_bf16 v[108:111], v[124:127], v[192:195], v[108:111]
	v_mfma_f32_16x16x32_bf16 v[104:107], v[132:135], v[192:195], v[104:107]
	v_mfma_f32_16x16x32_bf16 v[96:99], v[124:127], v[200:203], v[96:99]
	v_mfma_f32_16x16x32_bf16 v[88:91], v[132:135], v[200:203], v[88:91]
	v_mfma_f32_16x16x32_bf16 v[80:83], v[124:127], v[222:225], v[80:83]
	v_mfma_f32_16x16x32_bf16 v[72:75], v[132:135], v[222:225], v[72:75]
	v_mfma_f32_16x16x32_bf16 v[116:119], v[144:147], v[160:163], v[116:119]
	v_mfma_f32_16x16x32_bf16 v[112:115], v[152:155], v[160:163], v[112:115]
	v_mfma_f32_16x16x32_bf16 v[100:103], v[144:147], v[168:171], v[100:103]
	v_mfma_f32_16x16x32_bf16 v[92:95], v[152:155], v[168:171], v[92:95]
	v_mfma_f32_16x16x32_bf16 v[84:87], v[144:147], v[196:199], v[84:87]
	v_mfma_f32_16x16x32_bf16 v[76:79], v[152:155], v[196:199], v[76:79]
	v_mfma_f32_16x16x32_bf16 v[68:71], v[144:147], v[218:221], v[68:71]
	v_mfma_f32_16x16x32_bf16 v[64:67], v[152:155], v[218:221], v[64:67]
	v_mfma_f32_16x16x32_bf16 v[116:119], v[148:151], v[164:167], v[116:119]
	v_mfma_f32_16x16x32_bf16 v[112:115], v[156:159], v[164:167], v[112:115]
	v_mfma_f32_16x16x32_bf16 v[100:103], v[148:151], v[192:195], v[100:103]
	v_mfma_f32_16x16x32_bf16 v[92:95], v[156:159], v[192:195], v[92:95]
	v_mfma_f32_16x16x32_bf16 v[84:87], v[148:151], v[200:203], v[84:87]
	v_mfma_f32_16x16x32_bf16 v[76:79], v[156:159], v[200:203], v[76:79]
	v_mfma_f32_16x16x32_bf16 v[68:71], v[148:151], v[222:225], v[68:71]
	v_mfma_f32_16x16x32_bf16 v[64:67], v[156:159], v[222:225], v[64:67]
	s_barrier
	s_add_i32 s4, s64, s50
	v_lshl_add_u64 v[226:227], v[226:227], 0, s[36:37]
	s_mov_b32 m0, s4
	ds_read_b128 v[160:163], v217 offset:49152
	ds_read_b128 v[164:167], v217 offset:50176
	ds_read_b128 v[168:171], v217 offset:51200
	ds_read_b128 v[192:195], v217 offset:52224
	ds_read_b128 v[196:199], v217 offset:53248
	ds_read_b128 v[200:203], v217 offset:54272
	ds_read_b128 v[218:221], v217 offset:55296
	ds_read_b128 v[222:225], v217 offset:56320
	global_load_lds_dwordx4 v[226:227], off
	v_lshl_add_u64 v[226:227], v[228:229], 0, s[36:37]
	s_add_i32 m0, s4, 0x2000
	s_add_i32 s4, s65, s50
	global_load_lds_dwordx4 v[226:227], off
	v_lshl_add_u64 v[226:227], v[230:231], 0, s[36:37]
	s_mov_b32 m0, s4
	s_nop 0
	global_load_lds_dwordx4 v[226:227], off
	v_lshl_add_u64 v[226:227], v[232:233], 0, s[36:37]
	s_add_i32 m0, s4, 0x2000
	s_nop 0
	global_load_lds_dwordx4 v[226:227], off
	v_lshl_add_u64 v[226:227], v[234:235], 0, s[36:37]
	s_mov_b32 m0, s56
	s_nop 0
	global_load_lds_dwordx4 v[226:227], off
	v_lshl_add_u64 v[226:227], v[236:237], 0, s[36:37]
	s_mov_b32 m0, s57
	s_nop 0
	global_load_lds_dwordx4 v[226:227], off
	s_waitcnt vmcnt(8)
	s_waitcnt lgkmcnt(0)
	s_barrier
	s_waitcnt lgkmcnt(0)
	v_mfma_f32_16x16x32_bf16 v[60:63], v[120:123], v[160:163], v[60:63]
	v_mfma_f32_16x16x32_bf16 v[56:59], v[128:131], v[160:163], v[56:59]
	v_mfma_f32_16x16x32_bf16 v[48:51], v[120:123], v[168:171], v[48:51]
	v_mfma_f32_16x16x32_bf16 v[40:43], v[128:131], v[168:171], v[40:43]
	v_mfma_f32_16x16x32_bf16 v[32:35], v[120:123], v[196:199], v[32:35]
	v_mfma_f32_16x16x32_bf16 v[24:27], v[128:131], v[196:199], v[24:27]
	v_mfma_f32_16x16x32_bf16 v[16:19], v[120:123], v[218:221], v[16:19]
	v_mfma_f32_16x16x32_bf16 v[8:11], v[128:131], v[218:221], v[8:11]
	v_mfma_f32_16x16x32_bf16 v[60:63], v[124:127], v[164:167], v[60:63]
	v_mfma_f32_16x16x32_bf16 v[56:59], v[132:135], v[164:167], v[56:59]
	v_mfma_f32_16x16x32_bf16 v[48:51], v[124:127], v[192:195], v[48:51]
	v_mfma_f32_16x16x32_bf16 v[40:43], v[132:135], v[192:195], v[40:43]
	v_mfma_f32_16x16x32_bf16 v[32:35], v[124:127], v[200:203], v[32:35]
	v_mfma_f32_16x16x32_bf16 v[24:27], v[132:135], v[200:203], v[24:27]
	v_mfma_f32_16x16x32_bf16 v[16:19], v[124:127], v[222:225], v[16:19]
	v_mfma_f32_16x16x32_bf16 v[8:11], v[132:135], v[222:225], v[8:11]
	v_mfma_f32_16x16x32_bf16 v[52:55], v[144:147], v[160:163], v[52:55]
	v_mfma_f32_16x16x32_bf16 v[44:47], v[152:155], v[160:163], v[44:47]
	v_mfma_f32_16x16x32_bf16 v[36:39], v[144:147], v[168:171], v[36:39]
	v_mfma_f32_16x16x32_bf16 v[28:31], v[152:155], v[168:171], v[28:31]
	v_mfma_f32_16x16x32_bf16 v[20:23], v[144:147], v[196:199], v[20:23]
	v_mfma_f32_16x16x32_bf16 v[12:15], v[152:155], v[196:199], v[12:15]
	v_mfma_f32_16x16x32_bf16 v[4:7], v[144:147], v[218:221], v[4:7]
	v_mfma_f32_16x16x32_bf16 v[0:3], v[152:155], v[218:221], v[0:3]
	v_mfma_f32_16x16x32_bf16 v[52:55], v[148:151], v[164:167], v[52:55]
	v_mfma_f32_16x16x32_bf16 v[44:47], v[156:159], v[164:167], v[44:47]
	v_mfma_f32_16x16x32_bf16 v[36:39], v[148:151], v[192:195], v[36:39]
	v_mfma_f32_16x16x32_bf16 v[28:31], v[156:159], v[192:195], v[28:31]
	v_mfma_f32_16x16x32_bf16 v[20:23], v[148:151], v[200:203], v[20:23]
	v_mfma_f32_16x16x32_bf16 v[12:15], v[156:159], v[200:203], v[12:15]
	v_mfma_f32_16x16x32_bf16 v[4:7], v[148:151], v[222:225], v[4:7]
	v_mfma_f32_16x16x32_bf16 v[0:3], v[156:159], v[222:225], v[0:3]
	s_barrier
	s_add_u32 s46, s46, 0x100
	s_addc_u32 s47, s47, 0
	s_add_u32 s48, s48, 0x100
	s_addc_u32 s49, s49, 0
	s_cmp_ge_u32 s63, s35
	s_mov_b32 s4, s63
	s_cbranch_scc0 .LBB0_1412
	s_and_b64 vcc, exec, s[38:39]
	s_cbranch_vccz .LBB0_1415
	s_barrier
